# ACT epilogue (P5/P10): global_store_dwordx2 pairs widened to dwordx4 (layout 1: rows exchanged with v_permlane16_swap; layout 0: p=0 results parked in the wave's own LDS ring pieces and merged with p=
# speedup vs baseline: 1.0036x; 1.0005x over previous
.LBB0_875:
	s_or_b64 exec, exec, s[8:9]
	s_and_b32 s1, s51, 1
	s_bitcmp1_b32 s51, 0
	s_cselect_b64 s[72:73], -1, 0
	s_lshl_b32 s0, s0, 11
	s_xor_b32 s0, s0, 0x800
	s_add_i32 s50, s0, 0
	s_add_i32 s50, s50, 0x22400
	s_and_b32 s0, s51, 16
	s_bitcmp1_b32 s15, 0
	s_cselect_b32 s3, 0xc00, 0
	s_add_i32 s15, s3, 0
	s_add_i32 s15, s15, 0x23400
	v_or_b32_e32 v2, s1, v231
	s_cmp_eq_u32 s0, 0
	v_cmp_eq_u32_e64 s[8:9], 0, v2
	s_cbranch_scc1 .LBB0_971
	s_waitcnt lgkmcnt(0)
	s_barrier
	s_mov_b32 s98, 0xffff0000
	s_mov_b32 s99, 0xffff0000
	s_mov_b32 s100, 0xffff
	s_mov_b32 s101, 0xffff
	v_lshl_add_u32 v4, v206, 2, s15
	ds_read_b128 v[146:149], v4 offset:256
	ds_read_b128 v[134:137], v4 offset:768
	ds_read_b128 v[154:157], v4 offset:1280
	ds_read_b128 v[142:145], v4 offset:1792
	ds_read_b128 v[150:153], v4 offset:2304
	ds_read_b128 v[138:141], v4 offset:2816
	s_andn2_b64 vcc, exec, s[74:75]
	s_add_i32 s17, s50, 0x400
	s_cbranch_vccnz .LBB0_900
	s_waitcnt lgkmcnt(0)
	ds_read_b128 v[174:177], v4
	ds_read_b128 v[162:165], v4 offset:512
	ds_read_b128 v[178:181], v4 offset:1024
	ds_read_b128 v[166:169], v4 offset:1536
	ds_read_b128 v[170:173], v4 offset:2048
	ds_read_b128 v[158:161], v4 offset:2560
	s_and_b64 s[74:75], s[54:55], s[72:73]
	v_mov_b32_e32 v182, 0
	s_and_b64 vcc, exec, s[74:75]
	v_mov_b32_e32 v186, 0
	v_mov_b32_e32 v187, 0
	v_mov_b32_e32 v188, 0
	v_mov_b32_e32 v189, 0
	s_cbranch_vccnz .LBB0_879
	s_and_b64 s[0:1], s[54:55], exec
	s_cselect_b32 s0, s17, s33
	v_lshl_add_u32 v4, v228, 2, s0
	ds_read_b128 v[186:189], v4

.LBB0_885:
	v_pk_mul_f32 v[4:5], v[214:215], v[184:185]
	s_waitcnt lgkmcnt(0)
	v_pk_mul_f32 v[184:185], v[210:211], v[186:187]
	v_mul_f32_e32 v186, v10, v166
	v_pk_mul_f32 v[190:191], v[208:209], v[190:191]
	v_fmac_f32_dpp v186, v58, v162 row_shr:1 row_mask:0xf bank_mask:0xf
	v_mul_f32_e32 v187, v11, v167
	v_pk_mul_f32 v[182:183], v[210:211], v[182:183]
	v_fmac_f32_e32 v186, v162, v190
	v_fmac_f32_dpp v187, v59, v163 row_shr:1 row_mask:0xf bank_mask:0xf
	v_fmac_f32_e32 v221, v170, v182
	v_fmac_f32_e32 v220, v171, v183
	v_pk_mul_f32 v[182:183], v[214:215], v[188:189]
	v_fmac_f32 v186, v66, v158
	v_fmac_f32_e32 v187, v163, v191
	v_mul_f32_e32 v188, 0xbfb8aa3b, v186
	v_fmac_f32 v187, v67, v159
	v_exp_f32_e32 v188, v188
	v_mul_f32_e32 v191, 0xbfb8aa3b, v187
	v_exp_f32_e32 v191, v191
	v_mul_f32_e32 v189, v12, v168
	v_add_f32_e32 v188, 1.0, v188
	v_rcp_f32_e32 v188, v188
	v_add_f32_e32 v191, 1.0, v191
	v_rcp_f32_e32 v191, v191
	v_pk_mul_f32 v[192:193], v[212:213], v[192:193]
	v_fmac_f32_dpp v189, v60, v164 row_shr:1 row_mask:0xf bank_mask:0xf
	v_mul_f32_e32 v190, v13, v169
	v_fmac_f32_e32 v189, v164, v192
	v_fmac_f32_dpp v190, v61, v165 row_shr:1 row_mask:0xf bank_mask:0xf
	v_fmac_f32 v189, v68, v160
	v_mul_f32_e32 v186, v186, v188
	v_fmac_f32_e32 v190, v165, v193
	v_mul_f32_e32 v188, 0xbfb8aa3b, v189
	v_fmac_f32 v190, v69, v161
	v_mul_f32_e32 v187, v187, v191
	v_exp_f32_e32 v188, v188
	v_mul_f32_e32 v191, 0xbfb8aa3b, v190
	v_exp_f32_e32 v191, v191
	v_mul_f32_e32 v186, v195, v186
	v_add_f32_e32 v188, 1.0, v188
	v_rcp_f32_e32 v192, v188
	v_add_f32_e32 v188, 1.0, v191
	v_rcp_f32_e32 v191, v188
	v_mul_f32_e32 v187, v194, v187
	v_cvt_pk_bf16_f32 v122, v186, v187
	v_mul_f32_e32 v186, v189, v192
	v_mul_f32_e32 v187, v190, v191
	v_fmac_f32_e32 v197, v172, v4
	v_lshl_or_b32 v4, s16, 7, v206
	v_mul_f32_e32 v186, v249, v186
	v_mul_f32_e32 v187, v250, v187
	s_lshl_b32 s51, s14, 8
	v_fmac_f32_e32 v196, v173, v5
	v_ashrrev_i32_e32 v5, 31, v4
	v_cvt_pk_bf16_f32 v123, v186, v187
	v_add_u32_e32 v190, s51, v230
	v_mov_b64_e32 v[186:187], s[42:43]
	v_mad_i64_i32 v[190:191], s[0:1], v190, s21, v[186:187]
	v_lshlrev_b64 v[194:195], 1, v[4:5]
	v_lshl_add_u64 v[190:191], v[190:191], 0, v[194:195]
	v_mul_f32_e32 v188, v66, v166
	v_fmac_f32 v188, v10, v162
	v_mul_f32_e32 v189, v67, v167
	v_fmac_f32 v188, v62, v158
	v_fmac_f32 v189, v11, v163
	v_mul_f32_e32 v190, v68, v168
	v_mul_f32_e32 v192, 0xbfb8aa3b, v188
	v_exp_f32_e32 v192, v192
	v_fmac_f32 v189, v63, v159
	v_fmac_f32 v190, v12, v164
	v_mul_f32_e32 v191, v69, v169
	v_add_f32_e32 v192, 1.0, v192
	v_rcp_f32_e32 v192, v192
	v_fmac_f32 v190, v64, v160
	v_fmac_f32 v191, v13, v165
	s_nop 0
	v_mul_f32_e32 v188, v188, v192
	v_mul_f32_e32 v192, 0xbfb8aa3b, v189
	v_exp_f32_e32 v192, v192
	v_mul_f32_e32 v188, v248, v188
	v_fmac_f32 v191, v65, v161
	v_add_f32_e32 v192, 1.0, v192
	v_rcp_f32_e32 v192, v192
	s_nop 0
	v_mul_f32_e32 v189, v189, v192
	v_mul_f32_e32 v189, v247, v189
	v_cvt_pk_bf16_f32 v124, v188, v189
	v_mul_f32_e32 v189, 0xbfb8aa3b, v190
	v_exp_f32_e32 v189, v189
	s_nop 0
	v_add_f32_e32 v189, 1.0, v189
	v_rcp_f32_e32 v189, v189
	s_nop 0
	v_mul_f32_e32 v189, v190, v189
	v_mul_f32_e32 v190, 0xbfb8aa3b, v191
	v_exp_f32_e32 v190, v190
	v_mul_f32_e32 v189, v246, v189
	v_add_f32_e32 v190, 1.0, v190
	v_rcp_f32_e32 v190, v190
	s_nop 0
	v_mul_f32_e32 v190, v191, v190
	v_mul_f32_e32 v190, v245, v190
	v_cvt_pk_bf16_f32 v125, v189, v190
	s_nop 1
	v_permlane16_swap_b32 v122, v124
	v_permlane16_swap_b32 v123, v125
	v_cndmask_b32_e64 v190, v230, v232, s[98:99]
	v_add_u32_e32 v190, s51, v190
	v_mad_i64_i32 v[190:191], s[0:1], v190, s21, v[186:187]
	v_lshl_add_u64 v[190:191], v[190:191], 0, v[194:195]
	v_cndmask_b32_e64 v188, 0, -8, s[98:99]
	v_ashrrev_i32_e32 v189, 31, v188
	v_lshl_add_u64 v[190:191], v[190:191], 0, v[188:189]
	global_store_dwordx4 v[190:191], v[122:125], off
	v_mul_f32_e32 v188, v62, v166
	v_fmac_f32 v188, v66, v162
	v_mul_f32_e32 v189, v63, v167
	v_fmac_f32 v188, v58, v158
	v_fmac_f32 v189, v67, v163
	v_mul_f32_e32 v190, v64, v168
	v_mul_f32_e32 v192, 0xbfb8aa3b, v188
	v_exp_f32_e32 v192, v192
	v_fmac_f32 v189, v59, v159
	v_fmac_f32 v190, v68, v164
	v_mul_f32_e32 v191, v65, v169
	v_add_f32_e32 v192, 1.0, v192
	v_rcp_f32_e32 v192, v192
	v_fmac_f32 v190, v60, v160
	v_fmac_f32 v191, v69, v165
	s_nop 0
	v_mul_f32_e32 v188, v188, v192
	v_mul_f32_e32 v192, 0xbfb8aa3b, v189
	v_exp_f32_e32 v192, v192
	v_mul_f32_e32 v188, v225, v188
	v_fmac_f32 v191, v61, v161
	v_add_f32_e32 v192, 1.0, v192
	v_rcp_f32_e32 v192, v192
	s_nop 0
	v_mul_f32_e32 v189, v189, v192
	v_mul_f32_e32 v189, v224, v189
	v_cvt_pk_bf16_f32 v66, v188, v189
	v_mul_f32_e32 v189, 0xbfb8aa3b, v190
	v_exp_f32_e32 v189, v189
	s_nop 0
	v_add_f32_e32 v189, 1.0, v189
	v_rcp_f32_e32 v189, v189
	s_nop 0
	v_mul_f32_e32 v189, v190, v189
	v_mul_f32_e32 v190, 0xbfb8aa3b, v191
	v_exp_f32_e32 v190, v190
	v_mul_f32_e32 v189, v223, v189
	v_add_f32_e32 v190, 1.0, v190
	v_rcp_f32_e32 v190, v190
	s_nop 0
	v_mul_f32_e32 v190, v191, v190
	v_mul_f32_e32 v190, v222, v190
	v_cvt_pk_bf16_f32 v67, v189, v190
	v_add_u32_e32 v190, s51, v233
	v_mad_i64_i32 v[186:187], s[0:1], v190, s21, v[186:187]
	v_lshl_add_u64 v[186:187], v[186:187], 0, v[194:195]
	v_mul_f32_e32 v186, v58, v166
	v_fmac_f32 v186, v62, v162
	v_mul_f32_e32 v187, v61, v169
	v_fmac_f32_dpp v186, v10, v158 row_shl:1 row_mask:0xf bank_mask:0xf
	v_fmac_f32 v187, v65, v165
	s_or_b64 s[0:1], s[70:71], s[4:5]
	v_fmac_f32_e32 v186, v158, v184
	v_mul_f32_e32 v184, v59, v167
	v_fmac_f32 v184, v63, v163
	v_fmac_f32_dpp v187, v13, v161 row_shl:1 row_mask:0xf bank_mask:0xf
	s_nop 0
	v_fmac_f32_dpp v184, v11, v159 row_shl:1 row_mask:0xf bank_mask:0xf
	v_fmac_f32_e32 v187, v161, v183
	v_fmac_f32_e32 v184, v159, v185
	v_mul_f32_e32 v185, v60, v168
	v_fmac_f32 v185, v64, v164
	v_mul_f32_e32 v183, 0xbfb8aa3b, v184
	v_fmac_f32_dpp v185, v12, v160 row_shl:1 row_mask:0xf bank_mask:0xf
	v_exp_f32_e32 v183, v183
	v_fmac_f32_e32 v185, v160, v182
	v_mul_f32_e32 v182, 0xbfb8aa3b, v186
	v_exp_f32_e32 v182, v182
	v_add_f32_e32 v183, 1.0, v183
	v_rcp_f32_e32 v183, v183
	v_add_f32_e32 v182, 1.0, v182
	v_rcp_f32_e32 v182, v182
	v_mul_f32_e32 v183, v184, v183
	v_mul_f32_e32 v183, v220, v183
	v_mul_f32_e32 v184, 0xbfb8aa3b, v187
	v_mul_f32_e32 v182, v186, v182
	v_mul_f32_e32 v182, v221, v182
	v_cvt_pk_bf16_f32 v68, v182, v183
	v_mul_f32_e32 v183, 0xbfb8aa3b, v185
	v_exp_f32_e32 v183, v183
	v_exp_f32_e32 v184, v184
	v_add_f32_e32 v183, 1.0, v183
	v_rcp_f32_e32 v183, v183
	v_add_f32_e32 v184, 1.0, v184
	v_rcp_f32_e32 v184, v184
	v_mul_f32_e32 v183, v185, v183
	v_mul_f32_e32 v183, v197, v183
	v_mul_f32_e32 v184, v187, v184
	v_mul_f32_e32 v184, v196, v184
	v_cvt_pk_bf16_f32 v69, v183, v184
	s_nop 1
	v_permlane16_swap_b32 v66, v68
	v_permlane16_swap_b32 v67, v69
	s_or_b64 s[0:1], s[0:1], s[100:101]
	s_and_saveexec_b64 s[10:11], s[0:1]
	s_cbranch_execz .LBB0_887
	v_cndmask_b32_e64 v186, v233, v234, s[98:99]
	v_add_u32_e32 v186, s51, v186
	v_mov_b64_e32 v[184:185], s[42:43]
	v_mad_i64_i32 v[184:185], s[0:1], v186, s21, v[184:185]
	v_lshl_add_u64 v[184:185], v[4:5], 1, v[184:185]
	v_cndmask_b32_e64 v182, 0, -8, s[98:99]
	v_ashrrev_i32_e32 v183, 31, v182
	v_lshl_add_u64 v[184:185], v[184:185], 0, v[182:183]
	global_store_dwordx4 v[184:185], v[66:69], off

.LBB0_895:
	v_pk_mul_f32 v[184:185], v[214:215], v[184:185]
	s_waitcnt lgkmcnt(0)
	v_pk_mul_f32 v[190:191], v[208:209], v[190:191]
	v_fmac_f32_e32 v197, v172, v184
	v_fmac_f32_e32 v196, v173, v185
	v_pk_mul_f32 v[184:185], v[210:211], v[186:187]
	v_mul_f32_e32 v186, v30, v166
	v_fmac_f32_dpp v186, v34, v162 row_shr:1 row_mask:0xf bank_mask:0xf
	v_mul_f32_e32 v187, v31, v167
	v_pk_mul_f32 v[182:183], v[210:211], v[182:183]
	v_fmac_f32_e32 v186, v162, v190
	v_fmac_f32_dpp v187, v35, v163 row_shr:1 row_mask:0xf bank_mask:0xf
	v_fmac_f32_e32 v221, v170, v182
	v_fmac_f32_e32 v220, v171, v183
	v_pk_mul_f32 v[182:183], v[214:215], v[188:189]
	v_fmac_f32 v186, v42, v158
	v_fmac_f32_e32 v187, v163, v191
	v_mul_f32_e32 v188, 0xbfb8aa3b, v186
	v_fmac_f32 v187, v43, v159
	v_exp_f32_e32 v188, v188
	v_mul_f32_e32 v191, 0xbfb8aa3b, v187
	v_exp_f32_e32 v191, v191
	v_mul_f32_e32 v189, v32, v168
	v_add_f32_e32 v188, 1.0, v188
	v_rcp_f32_e32 v188, v188
	v_add_f32_e32 v191, 1.0, v191
	v_rcp_f32_e32 v191, v191
	v_pk_mul_f32 v[192:193], v[212:213], v[192:193]
	v_fmac_f32_dpp v189, v36, v164 row_shr:1 row_mask:0xf bank_mask:0xf
	v_mul_f32_e32 v190, v33, v169
	v_fmac_f32_e32 v189, v164, v192
	v_fmac_f32_dpp v190, v37, v165 row_shr:1 row_mask:0xf bank_mask:0xf
	v_fmac_f32 v189, v44, v160
	v_mul_f32_e32 v186, v186, v188
	v_fmac_f32_e32 v190, v165, v193
	v_mul_f32_e32 v188, 0xbfb8aa3b, v189
	v_fmac_f32 v190, v45, v161
	v_mul_f32_e32 v187, v187, v191
	v_exp_f32_e32 v188, v188
	v_mul_f32_e32 v191, 0xbfb8aa3b, v190
	v_exp_f32_e32 v191, v191
	v_mul_f32_e32 v186, v249, v186
	v_add_f32_e32 v188, 1.0, v188
	v_rcp_f32_e32 v192, v188
	v_add_f32_e32 v188, 1.0, v191
	v_rcp_f32_e32 v191, v188
	v_mul_f32_e32 v187, v250, v187
	v_cvt_pk_bf16_f32 v58, v186, v187
	v_mul_f32_e32 v186, v189, v192
	v_mul_f32_e32 v187, v190, v191
	v_mul_f32_e32 v186, v251, v186
	v_mul_f32_e32 v187, v252, v187
	v_cvt_pk_bf16_f32 v59, v186, v187
	v_add_u32_e32 v190, s51, v235
	v_mov_b64_e32 v[186:187], s[42:43]
	v_mad_i64_i32 v[190:191], s[0:1], v190, s21, v[186:187]
	v_lshl_add_u64 v[190:191], v[190:191], 0, v[194:195]
	v_mul_f32_e32 v188, v42, v166
	v_fmac_f32 v188, v30, v162
	v_mul_f32_e32 v189, v43, v167
	v_fmac_f32 v188, v38, v158
	v_fmac_f32 v189, v31, v163
	v_mul_f32_e32 v190, v44, v168
	v_mul_f32_e32 v192, 0xbfb8aa3b, v188
	v_exp_f32_e32 v192, v192
	v_fmac_f32 v189, v39, v159
	v_fmac_f32 v190, v32, v164
	v_mul_f32_e32 v191, v45, v169
	v_add_f32_e32 v192, 1.0, v192
	v_rcp_f32_e32 v192, v192
	v_fmac_f32 v190, v40, v160
	v_fmac_f32 v191, v33, v165
	s_nop 0
	v_mul_f32_e32 v188, v188, v192
	v_mul_f32_e32 v192, 0xbfb8aa3b, v189
	v_exp_f32_e32 v192, v192
	v_mul_f32_e32 v188, v248, v188
	v_fmac_f32 v191, v41, v161
	v_add_f32_e32 v192, 1.0, v192
	v_rcp_f32_e32 v192, v192
	s_nop 0
	v_mul_f32_e32 v189, v189, v192
	v_mul_f32_e32 v189, v247, v189
	v_cvt_pk_bf16_f32 v60, v188, v189
	v_mul_f32_e32 v189, 0xbfb8aa3b, v190
	v_exp_f32_e32 v189, v189
	s_nop 0
	v_add_f32_e32 v189, 1.0, v189
	v_rcp_f32_e32 v189, v189
	s_nop 0
	v_mul_f32_e32 v189, v190, v189
	v_mul_f32_e32 v190, 0xbfb8aa3b, v191
	v_exp_f32_e32 v190, v190
	v_mul_f32_e32 v189, v246, v189
	v_add_f32_e32 v190, 1.0, v190
	v_rcp_f32_e32 v190, v190
	s_nop 0
	v_mul_f32_e32 v190, v191, v190
	v_mul_f32_e32 v190, v245, v190
	v_cvt_pk_bf16_f32 v61, v189, v190
	s_nop 1
	v_permlane16_swap_b32 v58, v60
	v_permlane16_swap_b32 v59, v61
	v_cndmask_b32_e64 v190, v235, v236, s[98:99]
	v_add_u32_e32 v190, s51, v190
	v_mad_i64_i32 v[190:191], s[0:1], v190, s21, v[186:187]
	v_lshl_add_u64 v[190:191], v[190:191], 0, v[194:195]
	v_cndmask_b32_e64 v188, 0, -8, s[98:99]
	v_ashrrev_i32_e32 v189, 31, v188
	v_lshl_add_u64 v[190:191], v[190:191], 0, v[188:189]
	global_store_dwordx4 v[190:191], v[58:61], off
	v_mul_f32_e32 v188, v38, v166
	v_fmac_f32 v188, v42, v162
	v_mul_f32_e32 v189, v39, v167
	v_fmac_f32 v188, v34, v158
	v_fmac_f32 v189, v43, v163
	v_mul_f32_e32 v190, v40, v168
	v_mul_f32_e32 v192, 0xbfb8aa3b, v188
	v_exp_f32_e32 v192, v192
	v_fmac_f32 v189, v35, v159
	v_fmac_f32 v190, v44, v164
	v_mul_f32_e32 v191, v41, v169
	v_add_f32_e32 v192, 1.0, v192
	v_rcp_f32_e32 v192, v192
	v_fmac_f32 v190, v36, v160
	v_fmac_f32 v191, v45, v165
	s_nop 0
	v_mul_f32_e32 v188, v188, v192
	v_mul_f32_e32 v192, 0xbfb8aa3b, v189
	v_exp_f32_e32 v192, v192
	v_mul_f32_e32 v188, v225, v188
	v_fmac_f32 v191, v37, v161
	v_add_f32_e32 v192, 1.0, v192
	v_rcp_f32_e32 v192, v192
	s_nop 0
	v_mul_f32_e32 v189, v189, v192
	v_mul_f32_e32 v189, v224, v189
	v_cvt_pk_bf16_f32 v42, v188, v189
	v_mul_f32_e32 v189, 0xbfb8aa3b, v190
	v_exp_f32_e32 v189, v189
	s_nop 0
	v_add_f32_e32 v189, 1.0, v189
	v_rcp_f32_e32 v189, v189
	s_nop 0
	v_mul_f32_e32 v189, v190, v189
	v_mul_f32_e32 v190, 0xbfb8aa3b, v191
	v_exp_f32_e32 v190, v190
	v_mul_f32_e32 v189, v223, v189
	v_add_f32_e32 v190, 1.0, v190
	v_rcp_f32_e32 v190, v190
	s_nop 0
	v_mul_f32_e32 v190, v191, v190
	v_mul_f32_e32 v190, v222, v190
	v_cvt_pk_bf16_f32 v43, v189, v190
	v_add_u32_e32 v190, s51, v237
	v_mad_i64_i32 v[186:187], s[0:1], v190, s21, v[186:187]
	v_lshl_add_u64 v[186:187], v[186:187], 0, v[194:195]
	v_mul_f32_e32 v186, v34, v166
	v_fmac_f32 v186, v38, v162
	v_mul_f32_e32 v187, v37, v169
	v_fmac_f32_dpp v186, v30, v158 row_shl:1 row_mask:0xf bank_mask:0xf
	v_fmac_f32 v187, v41, v165
	s_or_b64 s[0:1], s[70:71], s[6:7]
	v_fmac_f32_e32 v186, v158, v184
	v_mul_f32_e32 v184, v35, v167
	v_fmac_f32 v184, v39, v163
	v_fmac_f32_dpp v187, v33, v161 row_shl:1 row_mask:0xf bank_mask:0xf
	s_nop 0
	v_fmac_f32_dpp v184, v31, v159 row_shl:1 row_mask:0xf bank_mask:0xf
	v_fmac_f32_e32 v187, v161, v183
	v_fmac_f32_e32 v184, v159, v185
	v_mul_f32_e32 v185, v36, v168
	v_fmac_f32 v185, v40, v164
	v_mul_f32_e32 v183, 0xbfb8aa3b, v184
	v_fmac_f32_dpp v185, v32, v160 row_shl:1 row_mask:0xf bank_mask:0xf
	v_exp_f32_e32 v183, v183
	v_fmac_f32_e32 v185, v160, v182
	v_mul_f32_e32 v182, 0xbfb8aa3b, v186
	v_exp_f32_e32 v182, v182
	v_add_f32_e32 v183, 1.0, v183
	v_rcp_f32_e32 v183, v183
	v_add_f32_e32 v182, 1.0, v182
	v_rcp_f32_e32 v182, v182
	v_mul_f32_e32 v183, v184, v183
	v_mul_f32_e32 v183, v220, v183
	v_mul_f32_e32 v184, 0xbfb8aa3b, v187
	v_mul_f32_e32 v182, v186, v182
	v_mul_f32_e32 v182, v221, v182
	v_cvt_pk_bf16_f32 v44, v182, v183
	v_mul_f32_e32 v183, 0xbfb8aa3b, v185
	v_exp_f32_e32 v183, v183
	v_exp_f32_e32 v184, v184
	v_add_f32_e32 v183, 1.0, v183
	v_rcp_f32_e32 v183, v183
	v_add_f32_e32 v184, 1.0, v184
	v_rcp_f32_e32 v184, v184
	v_mul_f32_e32 v183, v185, v183
	v_mul_f32_e32 v183, v197, v183
	v_mul_f32_e32 v184, v187, v184
	v_mul_f32_e32 v184, v196, v184
	v_cvt_pk_bf16_f32 v45, v183, v184
	s_nop 1
	v_permlane16_swap_b32 v42, v44
	v_permlane16_swap_b32 v43, v45
	s_or_b64 s[0:1], s[0:1], s[100:101]
	s_and_saveexec_b64 s[10:11], s[0:1]
	s_cbranch_execz .LBB0_897
	v_cndmask_b32_e64 v186, v237, v238, s[98:99]
	v_add_u32_e32 v186, s51, v186
	v_mov_b64_e32 v[184:185], s[42:43]
	v_mad_i64_i32 v[184:185], s[0:1], v186, s21, v[184:185]
	v_lshl_add_u64 v[184:185], v[4:5], 1, v[184:185]
	v_cndmask_b32_e64 v182, 0, -8, s[98:99]
	v_ashrrev_i32_e32 v183, 31, v182
	v_lshl_add_u64 v[184:185], v[184:185], 0, v[182:183]
	global_store_dwordx4 v[184:185], v[42:45], off

.LBB0_909:
	v_pk_mul_f32 v[160:161], v[214:215], v[160:161]
	s_waitcnt lgkmcnt(0)
	v_pk_mul_f32 v[166:167], v[208:209], v[166:167]
	v_fmac_f32_e32 v173, v152, v160
	v_fmac_f32_e32 v172, v153, v161
	v_pk_mul_f32 v[160:161], v[210:211], v[162:163]
	v_mul_f32_e32 v162, v142, v6
	v_fmac_f32_dpp v162, v46, v134 row_shr:1 row_mask:0xf bank_mask:0xf
	v_mul_f32_e32 v163, v143, v7
	v_pk_mul_f32 v[158:159], v[210:211], v[158:159]
	v_fmac_f32_e32 v162, v134, v166
	v_fmac_f32_dpp v163, v47, v135 row_shr:1 row_mask:0xf bank_mask:0xf
	v_fmac_f32_e32 v175, v150, v158
	v_fmac_f32_e32 v174, v151, v159
	v_pk_mul_f32 v[158:159], v[214:215], v[164:165]
	v_fmac_f32 v162, v54, v138
	v_fmac_f32_e32 v163, v135, v167
	v_mul_f32_e32 v164, 0xbfb8aa3b, v162
	v_fmac_f32 v163, v55, v139
	v_exp_f32_e32 v164, v164
	v_mul_f32_e32 v167, 0xbfb8aa3b, v163
	v_exp_f32_e32 v167, v167
	v_mul_f32_e32 v165, v144, v8
	v_add_f32_e32 v164, 1.0, v164
	v_rcp_f32_e32 v164, v164
	v_add_f32_e32 v167, 1.0, v167
	v_rcp_f32_e32 v167, v167
	v_pk_mul_f32 v[168:169], v[212:213], v[168:169]
	v_fmac_f32_dpp v165, v48, v136 row_shr:1 row_mask:0xf bank_mask:0xf
	v_mul_f32_e32 v166, v145, v9
	v_fmac_f32_e32 v165, v136, v168
	v_fmac_f32_dpp v166, v49, v137 row_shr:1 row_mask:0xf bank_mask:0xf
	v_mul_f32_e32 v162, v162, v164
	v_fmac_f32 v165, v56, v140
	v_fmac_f32_e32 v166, v137, v169
	v_mul_f32_e32 v5, v5, v162
	v_mul_f32_e32 v162, v163, v167
	v_mul_f32_e32 v163, 0xbfb8aa3b, v165
	v_fmac_f32 v166, v57, v141
	v_exp_f32_e32 v163, v163
	v_mul_f32_e32 v164, 0xbfb8aa3b, v166
	v_exp_f32_e32 v164, v164
	v_mul_f32_e32 v4, v4, v162
	v_add_f32_e32 v162, 1.0, v163
	v_rcp_f32_e32 v162, v162
	v_add_f32_e32 v163, 1.0, v164
	v_rcp_f32_e32 v163, v163
	v_cvt_pk_bf16_f32 v10, v5, v4
	v_mul_f32_e32 v4, v165, v162
	v_mul_f32_e32 v4, v170, v4
	v_mul_f32_e32 v5, v166, v163
	s_lshl_b32 s51, s14, 8
	v_mul_f32_e32 v5, v171, v5
	v_cvt_pk_bf16_f32 v11, v4, v5
	v_add_u32_e32 v4, s51, v230
	v_mov_b64_e32 v[162:163], s[42:43]
	s_lshl_b32 s65, s16, 7
	v_mad_i64_i32 v[166:167], s[0:1], v4, s21, v[162:163]
	s_ashr_i32 s0, s65, 31
	s_nop 0
	v_mov_b32_e32 v5, s0
	v_or_b32_e32 v4, s65, v206
	v_lshlrev_b64 v[170:171], 1, v[4:5]
	v_lshl_add_u64 v[166:167], v[166:167], 0, v[170:171]
	v_mul_f32_e32 v164, v54, v142
	v_fmac_f32 v164, v6, v134
	v_mul_f32_e32 v165, v55, v143
	v_fmac_f32 v164, v50, v138
	v_fmac_f32 v165, v7, v135
	v_mul_f32_e32 v166, v56, v144
	v_mul_f32_e32 v168, 0xbfb8aa3b, v164
	v_exp_f32_e32 v168, v168
	v_fmac_f32 v165, v51, v139
	v_fmac_f32 v166, v8, v136
	v_mul_f32_e32 v167, v57, v145
	v_add_f32_e32 v168, 1.0, v168
	v_rcp_f32_e32 v168, v168
	v_fmac_f32 v166, v52, v140
	v_fmac_f32 v167, v9, v137
	s_nop 0
	v_mul_f32_e32 v164, v164, v168
	v_mul_f32_e32 v168, 0xbfb8aa3b, v165
	v_exp_f32_e32 v168, v168
	v_mul_f32_e32 v164, v183, v164
	v_fmac_f32 v167, v53, v141
	v_add_f32_e32 v168, 1.0, v168
	v_rcp_f32_e32 v168, v168
	s_nop 0
	v_mul_f32_e32 v165, v165, v168
	v_mul_f32_e32 v165, v182, v165
	v_cvt_pk_bf16_f32 v12, v164, v165
	v_mul_f32_e32 v165, 0xbfb8aa3b, v166
	v_exp_f32_e32 v165, v165
	s_nop 0
	v_add_f32_e32 v165, 1.0, v165
	v_rcp_f32_e32 v165, v165
	s_nop 0
	v_mul_f32_e32 v165, v166, v165
	v_mul_f32_e32 v166, 0xbfb8aa3b, v167
	v_exp_f32_e32 v166, v166
	v_mul_f32_e32 v165, v181, v165
	v_add_f32_e32 v166, 1.0, v166
	v_rcp_f32_e32 v166, v166
	s_nop 0
	v_mul_f32_e32 v166, v167, v166
	v_mul_f32_e32 v166, v180, v166
	v_cvt_pk_bf16_f32 v13, v165, v166
	s_nop 1
	v_permlane16_swap_b32 v10, v12
	v_permlane16_swap_b32 v11, v13
	v_cndmask_b32_e64 v166, v230, v232, s[98:99]
	v_add_u32_e32 v166, s51, v166
	v_mad_i64_i32 v[166:167], s[0:1], v166, s21, v[162:163]
	v_lshl_add_u64 v[166:167], v[166:167], 0, v[170:171]
	v_cndmask_b32_e64 v164, 0, -8, s[98:99]
	v_ashrrev_i32_e32 v165, 31, v164
	v_lshl_add_u64 v[166:167], v[166:167], 0, v[164:165]
	global_store_dwordx4 v[166:167], v[10:13], off offset:128
	v_mul_f32_e32 v164, v50, v142
	v_fmac_f32 v164, v54, v134
	v_mul_f32_e32 v165, v51, v143
	v_fmac_f32 v164, v46, v138
	v_fmac_f32 v165, v55, v135
	v_mul_f32_e32 v166, v52, v144
	v_mul_f32_e32 v168, 0xbfb8aa3b, v164
	v_exp_f32_e32 v168, v168
	v_fmac_f32 v165, v47, v139
	v_fmac_f32 v166, v56, v136
	v_mul_f32_e32 v167, v53, v145
	v_add_f32_e32 v168, 1.0, v168
	v_rcp_f32_e32 v168, v168
	v_fmac_f32 v166, v48, v140
	v_fmac_f32 v167, v57, v137
	s_nop 0
	v_mul_f32_e32 v164, v164, v168
	v_mul_f32_e32 v168, 0xbfb8aa3b, v165
	v_exp_f32_e32 v168, v168
	v_mul_f32_e32 v164, v179, v164
	v_fmac_f32 v167, v49, v141
	v_add_f32_e32 v168, 1.0, v168
	v_rcp_f32_e32 v168, v168
	s_nop 0
	v_mul_f32_e32 v165, v165, v168
	v_mul_f32_e32 v165, v178, v165
	v_cvt_pk_bf16_f32 v10, v164, v165
	v_mul_f32_e32 v165, 0xbfb8aa3b, v166
	v_exp_f32_e32 v165, v165
	s_nop 0
	v_add_f32_e32 v165, 1.0, v165
	v_rcp_f32_e32 v165, v165
	s_nop 0
	v_mul_f32_e32 v165, v166, v165
	v_mul_f32_e32 v166, 0xbfb8aa3b, v167
	v_exp_f32_e32 v166, v166
	v_mul_f32_e32 v165, v177, v165
	v_add_f32_e32 v166, 1.0, v166
	v_rcp_f32_e32 v166, v166
	s_nop 0
	v_mul_f32_e32 v166, v167, v166
	v_mul_f32_e32 v166, v176, v166
	v_cvt_pk_bf16_f32 v11, v165, v166
	v_add_u32_e32 v166, s51, v233
	v_mad_i64_i32 v[162:163], s[0:1], v166, s21, v[162:163]
	v_lshl_add_u64 v[162:163], v[162:163], 0, v[170:171]
	v_mul_f32_e32 v162, v142, v46
	v_fmac_f32 v162, v50, v134
	v_mul_f32_e32 v163, v145, v49
	v_fmac_f32_dpp v162, v6, v138 row_shl:1 row_mask:0xf bank_mask:0xf
	v_fmac_f32 v163, v53, v137
	s_or_b64 s[0:1], s[70:71], s[4:5]
	v_fmac_f32_e32 v162, v138, v160
	v_mul_f32_e32 v160, v143, v47
	v_fmac_f32 v160, v51, v135
	v_fmac_f32_dpp v163, v9, v141 row_shl:1 row_mask:0xf bank_mask:0xf
	s_nop 0
	v_fmac_f32_dpp v160, v7, v139 row_shl:1 row_mask:0xf bank_mask:0xf
	v_fmac_f32_e32 v163, v141, v159
	v_fmac_f32_e32 v160, v139, v161
	v_mul_f32_e32 v161, v144, v48
	v_fmac_f32 v161, v52, v136
	v_mul_f32_e32 v159, 0xbfb8aa3b, v160
	v_fmac_f32_dpp v161, v8, v140 row_shl:1 row_mask:0xf bank_mask:0xf
	v_exp_f32_e32 v159, v159
	v_fmac_f32_e32 v161, v140, v158
	v_mul_f32_e32 v158, 0xbfb8aa3b, v162
	v_exp_f32_e32 v158, v158
	v_add_f32_e32 v159, 1.0, v159
	v_rcp_f32_e32 v159, v159
	v_add_f32_e32 v158, 1.0, v158
	v_rcp_f32_e32 v158, v158
	v_mul_f32_e32 v159, v160, v159
	v_mul_f32_e32 v159, v174, v159
	v_mul_f32_e32 v160, 0xbfb8aa3b, v163
	v_mul_f32_e32 v158, v162, v158
	v_mul_f32_e32 v158, v175, v158
	v_cvt_pk_bf16_f32 v12, v158, v159
	v_mul_f32_e32 v159, 0xbfb8aa3b, v161
	v_exp_f32_e32 v159, v159
	v_exp_f32_e32 v160, v160
	v_add_f32_e32 v159, 1.0, v159
	v_rcp_f32_e32 v159, v159
	v_add_f32_e32 v160, 1.0, v160
	v_rcp_f32_e32 v160, v160
	v_mul_f32_e32 v159, v161, v159
	v_mul_f32_e32 v159, v173, v159
	v_mul_f32_e32 v160, v163, v160
	v_mul_f32_e32 v160, v172, v160
	v_cvt_pk_bf16_f32 v13, v159, v160
	s_nop 1
	v_permlane16_swap_b32 v10, v12
	v_permlane16_swap_b32 v11, v13
	s_or_b64 s[0:1], s[0:1], s[100:101]
	s_and_saveexec_b64 s[10:11], s[0:1]
	s_cbranch_execz .LBB0_911
	v_cndmask_b32_e64 v162, v233, v234, s[98:99]
	v_add_u32_e32 v162, s51, v162
	v_mov_b64_e32 v[160:161], s[42:43]
	v_mad_i64_i32 v[160:161], s[0:1], v162, s21, v[160:161]
	v_lshl_add_u64 v[160:161], v[4:5], 1, v[160:161]
	v_cndmask_b32_e64 v158, 0, -8, s[98:99]
	v_ashrrev_i32_e32 v159, 31, v158
	v_lshl_add_u64 v[160:161], v[160:161], 0, v[158:159]
	global_store_dwordx4 v[160:161], v[10:13], off offset:128

.LBB0_919:
	v_pk_mul_f32 v[160:161], v[214:215], v[160:161]
	s_waitcnt lgkmcnt(0)
	v_pk_mul_f32 v[166:167], v[208:209], v[166:167]
	v_fmac_f32_e32 v173, v152, v160
	v_fmac_f32_e32 v172, v153, v161
	v_pk_mul_f32 v[160:161], v[210:211], v[162:163]
	v_mul_f32_e32 v162, v142, v14
	v_fmac_f32_dpp v162, v18, v134 row_shr:1 row_mask:0xf bank_mask:0xf
	v_mul_f32_e32 v163, v143, v15
	v_pk_mul_f32 v[158:159], v[210:211], v[158:159]
	v_fmac_f32_e32 v162, v134, v166
	v_fmac_f32_dpp v163, v19, v135 row_shr:1 row_mask:0xf bank_mask:0xf
	v_fmac_f32_e32 v175, v150, v158
	v_fmac_f32_e32 v174, v151, v159
	v_pk_mul_f32 v[158:159], v[214:215], v[164:165]
	v_fmac_f32 v162, v26, v138
	v_fmac_f32_e32 v163, v135, v167
	v_mul_f32_e32 v164, 0xbfb8aa3b, v162
	v_fmac_f32 v163, v27, v139
	v_exp_f32_e32 v164, v164
	v_mul_f32_e32 v167, 0xbfb8aa3b, v163
	v_exp_f32_e32 v167, v167
	v_mul_f32_e32 v165, v144, v16
	v_add_f32_e32 v164, 1.0, v164
	v_rcp_f32_e32 v164, v164
	v_add_f32_e32 v167, 1.0, v167
	v_rcp_f32_e32 v167, v167
	v_pk_mul_f32 v[168:169], v[212:213], v[168:169]
	v_fmac_f32_dpp v165, v20, v136 row_shr:1 row_mask:0xf bank_mask:0xf
	v_mul_f32_e32 v166, v145, v17
	v_fmac_f32_e32 v165, v136, v168
	v_fmac_f32_dpp v166, v21, v137 row_shr:1 row_mask:0xf bank_mask:0xf
	v_fmac_f32 v165, v28, v140
	v_mul_f32_e32 v162, v162, v164
	v_fmac_f32_e32 v166, v137, v169
	v_mul_f32_e32 v164, 0xbfb8aa3b, v165
	v_fmac_f32 v166, v29, v141
	v_mul_f32_e32 v163, v163, v167
	v_exp_f32_e32 v164, v164
	v_mul_f32_e32 v167, 0xbfb8aa3b, v166
	v_exp_f32_e32 v167, v167
	v_mul_f32_e32 v162, v184, v162
	v_add_f32_e32 v164, 1.0, v164
	v_rcp_f32_e32 v168, v164
	v_add_f32_e32 v164, 1.0, v167
	v_rcp_f32_e32 v167, v164
	v_mul_f32_e32 v163, v185, v163
	v_cvt_pk_bf16_f32 v10, v162, v163
	v_mul_f32_e32 v162, v165, v168
	v_mul_f32_e32 v163, v166, v167
	v_mul_f32_e32 v162, v186, v162
	v_mul_f32_e32 v163, v187, v163
	v_cvt_pk_bf16_f32 v11, v162, v163
	v_add_u32_e32 v166, s51, v235
	v_mov_b64_e32 v[162:163], s[42:43]
	v_mad_i64_i32 v[166:167], s[0:1], v166, s21, v[162:163]
	v_lshl_add_u64 v[166:167], v[166:167], 0, v[170:171]
	v_mul_f32_e32 v164, v26, v142
	v_fmac_f32 v164, v14, v134
	v_mul_f32_e32 v165, v27, v143
	v_fmac_f32 v164, v22, v138
	v_fmac_f32 v165, v15, v135
	v_mul_f32_e32 v166, v28, v144
	v_mul_f32_e32 v168, 0xbfb8aa3b, v164
	v_exp_f32_e32 v168, v168
	v_fmac_f32 v165, v23, v139
	v_fmac_f32 v166, v16, v136
	v_mul_f32_e32 v167, v29, v145
	v_add_f32_e32 v168, 1.0, v168
	v_rcp_f32_e32 v168, v168
	v_fmac_f32 v166, v24, v140
	v_fmac_f32 v167, v17, v137
	s_nop 0
	v_mul_f32_e32 v164, v164, v168
	v_mul_f32_e32 v168, 0xbfb8aa3b, v165
	v_exp_f32_e32 v168, v168
	v_mul_f32_e32 v164, v183, v164
	v_fmac_f32 v167, v25, v141
	v_add_f32_e32 v168, 1.0, v168
	v_rcp_f32_e32 v168, v168
	s_nop 0
	v_mul_f32_e32 v165, v165, v168
	v_mul_f32_e32 v165, v182, v165
	v_cvt_pk_bf16_f32 v12, v164, v165
	v_mul_f32_e32 v165, 0xbfb8aa3b, v166
	v_exp_f32_e32 v165, v165
	s_nop 0
	v_add_f32_e32 v165, 1.0, v165
	v_rcp_f32_e32 v165, v165
	s_nop 0
	v_mul_f32_e32 v165, v166, v165
	v_mul_f32_e32 v166, 0xbfb8aa3b, v167
	v_exp_f32_e32 v166, v166
	v_mul_f32_e32 v165, v181, v165
	v_add_f32_e32 v166, 1.0, v166
	v_rcp_f32_e32 v166, v166
	s_nop 0
	v_mul_f32_e32 v166, v167, v166
	v_mul_f32_e32 v166, v180, v166
	v_cvt_pk_bf16_f32 v13, v165, v166
	s_nop 1
	v_permlane16_swap_b32 v10, v12
	v_permlane16_swap_b32 v11, v13
	v_cndmask_b32_e64 v166, v235, v236, s[98:99]
	v_add_u32_e32 v166, s51, v166
	v_mad_i64_i32 v[166:167], s[0:1], v166, s21, v[162:163]
	v_lshl_add_u64 v[166:167], v[166:167], 0, v[170:171]
	v_cndmask_b32_e64 v164, 0, -8, s[98:99]
	v_ashrrev_i32_e32 v165, 31, v164
	v_lshl_add_u64 v[166:167], v[166:167], 0, v[164:165]
	global_store_dwordx4 v[166:167], v[10:13], off offset:128
	v_mul_f32_e32 v164, v22, v142
	v_fmac_f32 v164, v26, v134
	v_mul_f32_e32 v165, v23, v143
	v_fmac_f32 v164, v18, v138
	v_fmac_f32 v165, v27, v135
	v_mul_f32_e32 v166, v24, v144
	v_mul_f32_e32 v168, 0xbfb8aa3b, v164
	v_exp_f32_e32 v168, v168
	v_fmac_f32 v165, v19, v139
	v_fmac_f32 v166, v28, v136
	v_mul_f32_e32 v167, v25, v145
	v_add_f32_e32 v168, 1.0, v168
	v_rcp_f32_e32 v168, v168
	v_fmac_f32 v166, v20, v140
	v_fmac_f32 v167, v29, v137
	s_nop 0
	v_mul_f32_e32 v164, v164, v168
	v_mul_f32_e32 v168, 0xbfb8aa3b, v165
	v_exp_f32_e32 v168, v168
	v_mul_f32_e32 v164, v179, v164
	v_fmac_f32 v167, v21, v141
	v_add_f32_e32 v168, 1.0, v168
	v_rcp_f32_e32 v168, v168
	s_nop 0
	v_mul_f32_e32 v165, v165, v168
	v_mul_f32_e32 v165, v178, v165
	v_cvt_pk_bf16_f32 v10, v164, v165
	v_mul_f32_e32 v165, 0xbfb8aa3b, v166
	v_exp_f32_e32 v165, v165
	s_nop 0
	v_add_f32_e32 v165, 1.0, v165
	v_rcp_f32_e32 v165, v165
	s_nop 0
	v_mul_f32_e32 v165, v166, v165
	v_mul_f32_e32 v166, 0xbfb8aa3b, v167
	v_exp_f32_e32 v166, v166
	v_mul_f32_e32 v165, v177, v165
	v_add_f32_e32 v166, 1.0, v166
	v_rcp_f32_e32 v166, v166
	s_nop 0
	v_mul_f32_e32 v166, v167, v166
	v_mul_f32_e32 v166, v176, v166
	v_cvt_pk_bf16_f32 v11, v165, v166
	v_add_u32_e32 v166, s51, v237
	v_mad_i64_i32 v[162:163], s[0:1], v166, s21, v[162:163]
	v_lshl_add_u64 v[162:163], v[162:163], 0, v[170:171]
	v_mul_f32_e32 v162, v142, v18
	v_fmac_f32 v162, v22, v134
	v_mul_f32_e32 v163, v145, v21
	v_fmac_f32_dpp v162, v14, v138 row_shl:1 row_mask:0xf bank_mask:0xf
	v_fmac_f32 v163, v25, v137
	s_or_b64 s[0:1], s[70:71], s[6:7]
	v_fmac_f32_e32 v162, v138, v160
	v_mul_f32_e32 v160, v143, v19
	v_fmac_f32 v160, v23, v135
	v_fmac_f32_dpp v163, v17, v141 row_shl:1 row_mask:0xf bank_mask:0xf
	s_nop 0
	v_fmac_f32_dpp v160, v15, v139 row_shl:1 row_mask:0xf bank_mask:0xf
	v_fmac_f32_e32 v163, v141, v159
	v_fmac_f32_e32 v160, v139, v161
	v_mul_f32_e32 v161, v144, v20
	v_fmac_f32 v161, v24, v136
	v_mul_f32_e32 v159, 0xbfb8aa3b, v160
	v_fmac_f32_dpp v161, v16, v140 row_shl:1 row_mask:0xf bank_mask:0xf
	v_exp_f32_e32 v159, v159
	v_fmac_f32_e32 v161, v140, v158
	v_mul_f32_e32 v158, 0xbfb8aa3b, v162
	v_exp_f32_e32 v158, v158
	v_add_f32_e32 v159, 1.0, v159
	v_rcp_f32_e32 v159, v159
	v_add_f32_e32 v158, 1.0, v158
	v_rcp_f32_e32 v158, v158
	v_mul_f32_e32 v159, v160, v159
	v_mul_f32_e32 v159, v174, v159
	v_mul_f32_e32 v160, 0xbfb8aa3b, v163
	v_mul_f32_e32 v158, v162, v158
	v_mul_f32_e32 v158, v175, v158
	v_cvt_pk_bf16_f32 v12, v158, v159
	v_mul_f32_e32 v159, 0xbfb8aa3b, v161
	v_exp_f32_e32 v159, v159
	v_exp_f32_e32 v160, v160
	v_add_f32_e32 v159, 1.0, v159
	v_rcp_f32_e32 v159, v159
	v_add_f32_e32 v160, 1.0, v160
	v_rcp_f32_e32 v160, v160
	v_mul_f32_e32 v159, v161, v159
	v_mul_f32_e32 v159, v173, v159
	v_mul_f32_e32 v160, v163, v160
	v_mul_f32_e32 v160, v172, v160
	v_cvt_pk_bf16_f32 v13, v159, v160
	s_nop 1
	v_permlane16_swap_b32 v10, v12
	v_permlane16_swap_b32 v11, v13
	s_or_b64 s[0:1], s[0:1], s[100:101]
	s_and_saveexec_b64 s[10:11], s[0:1]
	s_cbranch_execz .LBB0_921
	v_cndmask_b32_e64 v162, v237, v238, s[98:99]
	v_add_u32_e32 v162, s51, v162
	v_mov_b64_e32 v[160:161], s[42:43]
	v_mad_i64_i32 v[160:161], s[0:1], v162, s21, v[160:161]
	v_lshl_add_u64 v[4:5], v[4:5], 1, v[160:161]
	v_cndmask_b32_e64 v158, 0, -8, s[98:99]
	v_ashrrev_i32_e32 v159, 31, v158
	v_lshl_add_u64 v[4:5], v[4:5], 0, v[158:159]
	global_store_dwordx4 v[4:5], v[10:13], off offset:128

.LBB0_925:
	s_waitcnt lgkmcnt(0)
	s_barrier
	v_readfirstlane_b32 s98, v0
	s_lshr_b32 s98, s98, 6
	s_lshl_b32 s98, s98, 10
	s_add_i32 m0, s98, 0x8000
	v_lshl_add_u32 v4, v228, 2, s15
	s_waitcnt lgkmcnt(0)
	ds_read_b128 v[170:173], v4
	ds_read_b128 v[146:149], v4 offset:16
	ds_read_b128 v[158:161], v4 offset:512
	ds_read_b128 v[134:137], v4 offset:528
	ds_read_b128 v[178:181], v4 offset:1024
	ds_read_b128 v[154:157], v4 offset:1040
	ds_read_b128 v[166:169], v4 offset:1536
	ds_read_b128 v[142:145], v4 offset:1552
	ds_read_b128 v[174:177], v4 offset:2048
	ds_read_b128 v[150:153], v4 offset:2064
	ds_read_b128 v[162:165], v4 offset:2560
	ds_read_b128 v[138:141], v4 offset:2576
	s_and_b64 s[10:11], s[54:55], s[72:73]
	s_add_i32 s65, s50, 0x400
	v_mov_b32_e32 v182, 0
	s_and_b64 vcc, exec, s[10:11]
	v_mov_b32_e32 v186, 0
	v_mov_b32_e32 v187, 0
	v_mov_b32_e32 v188, 0
	v_mov_b32_e32 v189, 0
	s_cbranch_vccnz .LBB0_927
	s_and_b64 s[0:1], s[54:55], exec
	s_cselect_b32 s0, s65, s33
	v_lshl_add_u32 v4, v228, 2, s0
	ds_read_b128 v[186:189], v4

.LBB0_933:
	v_pk_mul_f32 v[130:131], v[210:211], v[182:183]
	s_waitcnt lgkmcnt(0)
	v_pk_mul_f32 v[126:127], v[208:209], v[126:127]
	v_fmac_f32_e32 v188, v174, v130
	v_fmac_f32_e32 v186, v175, v131
	v_pk_mul_f32 v[130:131], v[210:211], v[122:123]
	v_mul_f32_e32 v122, v166, v70
	v_fmac_f32_dpp v122, v110, v158 row_shr:1 row_mask:0xf bank_mask:0xf
	v_mul_f32_e32 v123, v167, v71
	v_fmac_f32_e32 v122, v158, v126
	v_fmac_f32_dpp v123, v111, v159 row_shr:1 row_mask:0xf bank_mask:0xf
	v_pk_mul_f32 v[132:133], v[212:213], v[128:129]
	v_pk_mul_f32 v[128:129], v[214:215], v[124:125]
	v_fmac_f32 v122, v118, v162
	v_fmac_f32_e32 v123, v159, v127
	v_mul_f32_e32 v124, 0xbfb8aa3b, v122
	v_fmac_f32 v123, v119, v163
	v_exp_f32_e32 v124, v124
	v_mul_f32_e32 v127, 0xbfb8aa3b, v123
	v_exp_f32_e32 v127, v127
	v_mul_f32_e32 v125, v168, v72
	v_add_f32_e32 v124, 1.0, v124
	v_rcp_f32_e32 v124, v124
	v_add_f32_e32 v127, 1.0, v127
	v_rcp_f32_e32 v127, v127
	v_fmac_f32_dpp v125, v112, v160 row_shr:1 row_mask:0xf bank_mask:0xf
	v_mul_f32_e32 v126, v169, v73
	v_fmac_f32_e32 v125, v160, v132
	v_fmac_f32_dpp v126, v113, v161 row_shr:1 row_mask:0xf bank_mask:0xf
	v_fmac_f32 v125, v120, v164
	v_mul_f32_e32 v122, v122, v124
	v_fmac_f32_e32 v126, v161, v133
	v_mul_f32_e32 v124, 0xbfb8aa3b, v125
	v_fmac_f32 v126, v121, v165
	v_mul_f32_e32 v123, v123, v127
	v_exp_f32_e32 v124, v124
	v_mul_f32_e32 v127, 0xbfb8aa3b, v126
	v_exp_f32_e32 v127, v127
	v_mul_f32_e32 v122, v221, v122
	v_add_f32_e32 v124, 1.0, v124
	v_rcp_f32_e32 v132, v124
	v_add_f32_e32 v124, 1.0, v127
	v_rcp_f32_e32 v127, v124
	v_pk_mul_f32 v[4:5], v[214:215], v[184:185]
	v_mul_f32_e32 v123, v220, v123
	v_cvt_pk_bf16_f32 v124, v122, v123
	v_mul_f32_e32 v122, v125, v132
	v_fmac_f32_e32 v187, v176, v4
	v_lshl_or_b32 v4, s16, 7, v228
	v_mul_f32_e32 v122, v222, v122
	v_mul_f32_e32 v123, v126, v127
	s_lshl_b32 s51, s14, 8
	v_fmac_f32_e32 v189, v177, v5
	v_ashrrev_i32_e32 v5, 31, v4
	v_mul_f32_e32 v123, v223, v123
	v_cvt_pk_bf16_f32 v125, v122, v123
	v_add_u32_e32 v122, s51, v230
	v_mov_b64_e32 v[132:133], s[42:43]
	v_mad_i64_i32 v[122:123], s[0:1], v122, s21, v[132:133]
	v_lshlrev_b64 v[126:127], 1, v[4:5]
	v_lshl_add_u64 v[122:123], v[122:123], 0, v[126:127]
	ds_write_addtid_b32 v124 offset:0
	ds_write_addtid_b32 v125 offset:256
	v_mul_f32_e32 v124, v118, v166
	v_fmac_f32 v124, v70, v158
	v_mul_f32_e32 v125, v119, v167
	v_fmac_f32 v124, v114, v162
	v_fmac_f32 v125, v71, v159
	v_mul_f32_e32 v183, v120, v168
	v_mul_f32_e32 v182, 0xbfb8aa3b, v124
	v_exp_f32_e32 v182, v182
	v_fmac_f32 v125, v115, v163
	v_fmac_f32 v183, v72, v160
	v_mul_f32_e32 v184, v121, v169
	v_add_f32_e32 v182, 1.0, v182
	v_rcp_f32_e32 v182, v182
	v_fmac_f32 v183, v116, v164
	v_fmac_f32 v184, v73, v161
	s_nop 0
	v_mul_f32_e32 v124, v124, v182
	v_mul_f32_e32 v182, 0xbfb8aa3b, v125
	v_exp_f32_e32 v182, v182
	v_mul_f32_e32 v124, v197, v124
	v_fmac_f32 v184, v117, v165
	v_add_f32_e32 v182, 1.0, v182
	v_rcp_f32_e32 v182, v182
	s_nop 0
	v_mul_f32_e32 v125, v125, v182
	v_mul_f32_e32 v125, v196, v125
	v_cvt_pk_bf16_f32 v182, v124, v125
	v_mul_f32_e32 v124, 0xbfb8aa3b, v183
	v_exp_f32_e32 v124, v124
	v_mul_f32_e32 v125, 0xbfb8aa3b, v184
	v_exp_f32_e32 v125, v125
	v_add_f32_e32 v124, 1.0, v124
	v_rcp_f32_e32 v124, v124
	v_add_f32_e32 v125, 1.0, v125
	v_rcp_f32_e32 v125, v125
	v_mul_f32_e32 v124, v183, v124
	v_mul_f32_e32 v124, v195, v124
	v_mul_f32_e32 v125, v184, v125
	v_mul_f32_e32 v125, v194, v125
	v_cvt_pk_bf16_f32 v183, v124, v125
	v_add_u32_e32 v124, s51, v232
	v_mad_i64_i32 v[124:125], s[0:1], v124, s21, v[132:133]
	v_lshl_add_u64 v[124:125], v[124:125], 0, v[126:127]
	ds_write_addtid_b32 v182 offset:512
	ds_write_addtid_b32 v183 offset:768
	v_mul_f32_e32 v182, v114, v166
	v_fmac_f32 v182, v118, v158
	v_mul_f32_e32 v118, v115, v167
	v_fmac_f32 v118, v119, v159
	v_mul_f32_e32 v119, v116, v168
	v_mul_f32_e32 v183, v117, v169
	v_fmac_f32 v182, v110, v162
	v_fmac_f32 v118, v111, v163
	v_fmac_f32 v119, v120, v160
	v_fmac_f32 v183, v121, v161
	s_nop 0
	v_mul_f32_e32 v120, 0xbfb8aa3b, v182
	v_mul_f32_e32 v121, 0xbfb8aa3b, v118
	v_exp_f32_e32 v120, v120
	v_exp_f32_e32 v121, v121
	v_fmac_f32 v119, v112, v164
	v_fmac_f32 v183, v113, v165
	v_add_f32_e32 v120, 1.0, v120
	v_add_f32_e32 v121, 1.0, v121
	v_rcp_f32_e32 v120, v120
	v_rcp_f32_e32 v121, v121
	v_mul_f32_e32 v120, v182, v120
	v_mul_f32_e32 v118, v118, v121
	v_mul_f32_e32 v120, v193, v120
	v_mul_f32_e32 v118, v192, v118
	v_cvt_pk_bf16_f32 v120, v120, v118
	v_mul_f32_e32 v118, 0xbfb8aa3b, v119
	v_exp_f32_e32 v118, v118
	s_nop 0
	v_add_f32_e32 v118, 1.0, v118
	v_rcp_f32_e32 v118, v118
	s_nop 0
	v_mul_f32_e32 v118, v119, v118
	v_mul_f32_e32 v119, 0xbfb8aa3b, v183
	v_exp_f32_e32 v119, v119
	v_mul_f32_e32 v118, v191, v118
	v_add_f32_e32 v119, 1.0, v119
	v_rcp_f32_e32 v119, v119
	s_nop 0
	v_mul_f32_e32 v119, v183, v119
	v_mul_f32_e32 v119, v190, v119
	v_cvt_pk_bf16_f32 v121, v118, v119
	v_add_u32_e32 v118, s51, v233
	v_mad_i64_i32 v[118:119], s[0:1], v118, s21, v[132:133]
	v_lshl_add_u64 v[118:119], v[118:119], 0, v[126:127]
	ds_write_addtid_b32 v120 offset:8192
	ds_write_addtid_b32 v121 offset:8448
	v_mul_f32_e32 v110, v166, v110
	v_fmac_f32 v110, v114, v158
	v_mul_f32_e32 v111, v167, v111
	v_fmac_f32_dpp v110, v70, v162 row_shl:1 row_mask:0xf bank_mask:0xf
	v_fmac_f32 v111, v115, v159
	v_mul_f32_e32 v112, v168, v112
	v_fmac_f32_e32 v110, v162, v130
	v_fmac_f32_dpp v111, v71, v163 row_shl:1 row_mask:0xf bank_mask:0xf
	v_mul_f32_e32 v114, 0xbfb8aa3b, v110
	v_fmac_f32_e32 v111, v163, v131
	v_exp_f32_e32 v114, v114
	v_mul_f32_e32 v115, 0xbfb8aa3b, v111
	v_exp_f32_e32 v115, v115
	v_fmac_f32 v112, v116, v160
	v_add_f32_e32 v114, 1.0, v114
	v_rcp_f32_e32 v114, v114
	v_add_f32_e32 v115, 1.0, v115
	v_mul_f32_e32 v113, v169, v113
	v_rcp_f32_e32 v115, v115
	v_fmac_f32_dpp v112, v72, v164 row_shl:1 row_mask:0xf bank_mask:0xf
	v_fmac_f32 v113, v117, v161
	v_mul_f32_e32 v110, v110, v114
	v_fmac_f32_e32 v112, v164, v128
	v_fmac_f32_dpp v113, v73, v165 row_shl:1 row_mask:0xf bank_mask:0xf
	v_mul_f32_e32 v114, 0xbfb8aa3b, v112
	v_fmac_f32_e32 v113, v165, v129
	v_mul_f32_e32 v111, v111, v115
	v_exp_f32_e32 v114, v114
	v_mul_f32_e32 v115, 0xbfb8aa3b, v113
	v_exp_f32_e32 v115, v115
	v_mul_f32_e32 v110, v188, v110
	v_add_f32_e32 v114, 1.0, v114
	v_rcp_f32_e32 v114, v114
	v_add_f32_e32 v115, 1.0, v115
	v_rcp_f32_e32 v115, v115
	v_mul_f32_e32 v111, v186, v111
	v_cvt_pk_bf16_f32 v110, v110, v111
	v_mul_f32_e32 v111, v112, v114
	v_mul_f32_e32 v111, v187, v111
	v_mul_f32_e32 v112, v113, v115
	s_or_b64 s[76:77], s[70:71], s[4:5]
	v_add_u32_e32 v120, s51, v234
	v_mul_f32_e32 v112, v189, v112
	v_cvt_pk_bf16_f32 v111, v111, v112
	s_and_saveexec_b64 s[10:11], s[76:77]
	s_cbranch_execz .LBB0_935
	v_mov_b64_e32 v[112:113], s[42:43]
	v_mad_i64_i32 v[112:113], s[0:1], v120, s21, v[112:113]
	v_lshl_add_u64 v[112:113], v[4:5], 1, v[112:113]
	ds_write_addtid_b32 v110 offset:8704
	ds_write_addtid_b32 v111 offset:8960

.LBB0_943:
	v_pk_mul_f32 v[102:103], v[214:215], v[112:113]
	v_pk_mul_f32 v[110:111], v[210:211], v[110:111]
	v_fmac_f32_e32 v107, v176, v102
	v_fmac_f32_e32 v104, v177, v103
	s_waitcnt lgkmcnt(0)
	v_pk_mul_f32 v[102:103], v[212:213], v[100:101]
	v_pk_mul_f32 v[100:101], v[210:211], v[94:95]
	v_mul_f32_e32 v94, v166, v74
	v_fmac_f32_e32 v108, v174, v110
	v_fmac_f32_e32 v106, v175, v111
	v_pk_mul_f32 v[110:111], v[208:209], v[98:99]
	v_fmac_f32_dpp v94, v78, v158 row_shr:1 row_mask:0xf bank_mask:0xf
	v_mul_f32_e32 v95, v167, v75
	v_fmac_f32_e32 v94, v158, v110
	v_fmac_f32_dpp v95, v79, v159 row_shr:1 row_mask:0xf bank_mask:0xf
	v_pk_mul_f32 v[98:99], v[214:215], v[96:97]
	v_fmac_f32 v94, v90, v162
	v_fmac_f32_e32 v95, v159, v111
	v_mul_f32_e32 v96, 0xbfb8aa3b, v94
	v_fmac_f32 v95, v91, v163
	v_exp_f32_e32 v96, v96
	v_mul_f32_e32 v105, 0xbfb8aa3b, v95
	v_mul_f32_e32 v97, v168, v76
	v_exp_f32_e32 v105, v105
	v_fmac_f32_dpp v97, v80, v160 row_shr:1 row_mask:0xf bank_mask:0xf
	v_add_f32_e32 v96, 1.0, v96
	v_fmac_f32_e32 v97, v160, v102
	v_mul_f32_e32 v102, v169, v77
	v_fmac_f32_dpp v102, v81, v161 row_shr:1 row_mask:0xf bank_mask:0xf
	v_rcp_f32_e32 v96, v96
	v_fmac_f32_e32 v102, v161, v103
	v_add_f32_e32 v103, 1.0, v105
	v_rcp_f32_e32 v103, v103
	v_fmac_f32 v97, v92, v164
	v_mul_f32_e32 v94, v94, v96
	v_mul_f32_e32 v96, 0xbfb8aa3b, v97
	v_fmac_f32 v102, v93, v165
	v_mul_f32_e32 v95, v95, v103
	v_exp_f32_e32 v96, v96
	v_mul_f32_e32 v103, 0xbfb8aa3b, v102
	v_exp_f32_e32 v103, v103
	v_mul_f32_e32 v94, v131, v94
	v_add_f32_e32 v96, 1.0, v96
	v_rcp_f32_e32 v105, v96
	v_add_f32_e32 v96, 1.0, v103
	v_rcp_f32_e32 v103, v96
	v_mul_f32_e32 v95, v132, v95
	v_cvt_pk_bf16_f32 v96, v94, v95
	v_mul_f32_e32 v94, v97, v105
	v_mul_f32_e32 v94, v133, v94
	v_mul_f32_e32 v95, v102, v103
	v_mul_f32_e32 v95, v182, v95
	v_cvt_pk_bf16_f32 v97, v94, v95
	v_add_u32_e32 v94, s51, v235
	v_mov_b64_e32 v[102:103], s[42:43]
	v_mad_i64_i32 v[94:95], s[0:1], v94, s21, v[102:103]
	v_lshl_add_u64 v[94:95], v[94:95], 0, v[126:127]
	ds_write_addtid_b32 v96 offset:16384
	ds_write_addtid_b32 v97 offset:16640
	v_mul_f32_e32 v96, v90, v166
	v_fmac_f32 v96, v74, v158
	v_mul_f32_e32 v97, v91, v167
	v_fmac_f32 v96, v86, v162
	v_fmac_f32 v97, v75, v159
	v_mul_f32_e32 v105, v92, v168
	v_mul_f32_e32 v110, 0xbfb8aa3b, v96
	v_exp_f32_e32 v110, v110
	v_fmac_f32 v97, v87, v163
	v_fmac_f32 v105, v76, v160
	v_mul_f32_e32 v109, v93, v169
	v_add_f32_e32 v110, 1.0, v110
	v_rcp_f32_e32 v110, v110
	v_fmac_f32 v105, v88, v164
	v_fmac_f32 v109, v77, v161
	s_nop 0
	v_mul_f32_e32 v96, v96, v110
	v_mul_f32_e32 v110, 0xbfb8aa3b, v97
	v_exp_f32_e32 v110, v110
	v_mul_f32_e32 v96, v130, v96
	v_fmac_f32 v109, v89, v165
	v_add_f32_e32 v110, 1.0, v110
	v_rcp_f32_e32 v110, v110
	s_nop 0
	v_mul_f32_e32 v97, v97, v110
	v_mul_f32_e32 v97, v129, v97
	v_cvt_pk_bf16_f32 v110, v96, v97
	v_mul_f32_e32 v96, 0xbfb8aa3b, v105
	v_exp_f32_e32 v96, v96
	v_mul_f32_e32 v97, 0xbfb8aa3b, v109
	v_exp_f32_e32 v97, v97
	v_add_f32_e32 v96, 1.0, v96
	v_rcp_f32_e32 v96, v96
	v_add_f32_e32 v97, 1.0, v97
	v_rcp_f32_e32 v97, v97
	v_mul_f32_e32 v96, v105, v96
	v_mul_f32_e32 v96, v128, v96
	v_mul_f32_e32 v97, v109, v97
	v_mul_f32_e32 v97, v121, v97
	v_cvt_pk_bf16_f32 v111, v96, v97
	v_add_u32_e32 v96, s51, v236
	v_mad_i64_i32 v[96:97], s[0:1], v96, s21, v[102:103]
	v_lshl_add_u64 v[96:97], v[96:97], 0, v[126:127]
	ds_write_addtid_b32 v110 offset:16896
	ds_write_addtid_b32 v111 offset:17152
	v_mul_f32_e32 v105, v86, v166
	v_fmac_f32 v105, v90, v158
	v_mul_f32_e32 v90, v87, v167
	v_fmac_f32 v90, v91, v159
	v_mul_f32_e32 v91, v88, v168
	v_mul_f32_e32 v109, v89, v169
	v_fmac_f32 v105, v78, v162
	v_fmac_f32 v90, v79, v163
	v_fmac_f32 v91, v92, v160
	v_fmac_f32 v109, v93, v161
	s_nop 0
	v_mul_f32_e32 v92, 0xbfb8aa3b, v105
	v_mul_f32_e32 v93, 0xbfb8aa3b, v90
	v_exp_f32_e32 v92, v92
	v_exp_f32_e32 v93, v93
	v_fmac_f32 v91, v80, v164
	v_fmac_f32 v109, v81, v165
	v_add_f32_e32 v92, 1.0, v92
	v_add_f32_e32 v93, 1.0, v93
	v_rcp_f32_e32 v92, v92
	v_rcp_f32_e32 v93, v93
	v_mul_f32_e32 v92, v105, v92
	v_mul_f32_e32 v90, v90, v93
	v_mul_f32_e32 v92, v117, v92
	v_mul_f32_e32 v90, v116, v90
	v_cvt_pk_bf16_f32 v92, v92, v90
	v_mul_f32_e32 v90, 0xbfb8aa3b, v91
	v_exp_f32_e32 v90, v90
	s_nop 0
	v_add_f32_e32 v90, 1.0, v90
	v_rcp_f32_e32 v90, v90
	s_nop 0
	v_mul_f32_e32 v90, v91, v90
	v_mul_f32_e32 v91, 0xbfb8aa3b, v109
	v_exp_f32_e32 v91, v91
	v_mul_f32_e32 v90, v115, v90
	v_add_f32_e32 v91, 1.0, v91
	v_rcp_f32_e32 v91, v91
	s_nop 0
	v_mul_f32_e32 v91, v109, v91
	v_mul_f32_e32 v91, v114, v91
	v_cvt_pk_bf16_f32 v93, v90, v91
	v_add_u32_e32 v90, s51, v237
	v_mad_i64_i32 v[90:91], s[0:1], v90, s21, v[102:103]
	v_lshl_add_u64 v[90:91], v[90:91], 0, v[126:127]
	ds_write_addtid_b32 v92 offset:24576
	ds_write_addtid_b32 v93 offset:24832
	v_mul_f32_e32 v78, v166, v78
	v_fmac_f32 v78, v86, v158
	s_or_b64 s[70:71], s[70:71], s[6:7]
	v_fmac_f32_dpp v78, v74, v162 row_shl:1 row_mask:0xf bank_mask:0xf
	v_mul_f32_e32 v74, v167, v79
	v_fmac_f32 v74, v87, v159
	v_fmac_f32_e32 v78, v162, v100
	v_fmac_f32_dpp v74, v75, v163 row_shl:1 row_mask:0xf bank_mask:0xf
	v_mul_f32_e32 v79, 0xbfb8aa3b, v78
	v_fmac_f32_e32 v74, v163, v101
	v_mul_f32_e32 v75, v168, v80
	v_exp_f32_e32 v79, v79
	v_mul_f32_e32 v80, 0xbfb8aa3b, v74
	v_fmac_f32 v75, v88, v160
	v_exp_f32_e32 v80, v80
	v_fmac_f32_dpp v75, v76, v164 row_shl:1 row_mask:0xf bank_mask:0xf
	v_mul_f32_e32 v76, v169, v81
	v_fmac_f32 v76, v89, v161
	v_fmac_f32_e32 v75, v164, v98
	v_fmac_f32_dpp v76, v77, v165 row_shl:1 row_mask:0xf bank_mask:0xf
	v_add_f32_e32 v77, 1.0, v79
	v_rcp_f32_e32 v77, v77
	v_add_f32_e32 v79, 1.0, v80
	v_rcp_f32_e32 v79, v79
	v_fmac_f32_e32 v76, v165, v99
	v_mul_f32_e32 v77, v78, v77
	v_mul_f32_e32 v78, 0xbfb8aa3b, v75
	v_mul_f32_e32 v74, v74, v79
	v_exp_f32_e32 v78, v78
	v_mul_f32_e32 v79, 0xbfb8aa3b, v76
	v_exp_f32_e32 v79, v79
	v_mul_f32_e32 v74, v106, v74
	v_add_f32_e32 v78, 1.0, v78
	v_rcp_f32_e32 v78, v78
	v_add_f32_e32 v79, 1.0, v79
	v_rcp_f32_e32 v79, v79
	v_mul_f32_e32 v77, v108, v77
	v_mul_f32_e32 v75, v75, v78
	v_mul_f32_e32 v75, v107, v75
	v_mul_f32_e32 v76, v76, v79
	v_add_u32_e32 v78, s51, v238
	v_cvt_pk_bf16_f32 v74, v77, v74
	v_mul_f32_e32 v76, v104, v76
	v_cvt_pk_bf16_f32 v75, v75, v76
	s_and_saveexec_b64 s[16:17], s[70:71]
	s_cbranch_execz .LBB0_945
	v_mov_b64_e32 v[76:77], s[42:43]
	v_mad_i64_i32 v[76:77], s[0:1], v78, s21, v[76:77]
	v_lshl_add_u64 v[76:77], v[4:5], 1, v[76:77]
	ds_write_addtid_b32 v74 offset:25088
	ds_write_addtid_b32 v75 offset:25344

.LBB0_955:
	v_pk_mul_f32 v[70:71], v[210:211], v[70:71]
	s_waitcnt lgkmcnt(0)
	ds_read_addtid_b32 v98 offset:0
	ds_read_addtid_b32 v99 offset:256
	v_pk_mul_f32 v[62:63], v[208:209], v[62:63]
	v_fmac_f32_e32 v68, v150, v70
	v_mul_f32_e32 v70, v142, v6
	v_fmac_f32_dpp v70, v46, v134 row_shr:1 row_mask:0xf bank_mask:0xf
	v_pk_mul_f32 v[72:73], v[214:215], v[72:73]
	v_fmac_f32_e32 v70, v134, v62
	v_mul_f32_e32 v62, v143, v7
	v_fmac_f32_dpp v62, v47, v135 row_shr:1 row_mask:0xf bank_mask:0xf
	v_fmac_f32_e32 v66, v151, v71
	v_fmac_f32 v70, v54, v138
	v_fmac_f32_e32 v62, v135, v63
	v_mul_f32_e32 v71, 0xbfb8aa3b, v70
	v_fmac_f32_e32 v67, v152, v72
	v_fmac_f32 v62, v55, v139
	v_mul_f32_e32 v63, v144, v8
	v_exp_f32_e32 v71, v71
	v_mul_f32_e32 v72, 0xbfb8aa3b, v62
	v_pk_mul_f32 v[64:65], v[212:213], v[64:65]
	v_fmac_f32_dpp v63, v48, v136 row_shr:1 row_mask:0xf bank_mask:0xf
	v_exp_f32_e32 v72, v72
	v_fmac_f32_e32 v63, v136, v64
	v_mul_f32_e32 v64, v145, v9
	v_fmac_f32_dpp v64, v49, v137 row_shr:1 row_mask:0xf bank_mask:0xf
	v_fmac_f32 v63, v56, v140
	v_fmac_f32_e32 v69, v153, v73
	v_fmac_f32_e32 v64, v137, v65
	v_add_f32_e32 v65, 1.0, v71
	v_rcp_f32_e32 v65, v65
	v_add_f32_e32 v71, 1.0, v72
	v_rcp_f32_e32 v71, v71
	v_fmac_f32 v64, v57, v141
	v_mul_f32_e32 v65, v70, v65
	v_mul_f32_e32 v70, 0xbfb8aa3b, v63
	v_mul_f32_e32 v62, v62, v71
	v_exp_f32_e32 v70, v70
	v_mul_f32_e32 v71, 0xbfb8aa3b, v64
	v_exp_f32_e32 v71, v71
	v_mul_f32_e32 v62, v83, v62
	v_add_f32_e32 v70, 1.0, v70
	v_rcp_f32_e32 v70, v70
	v_add_f32_e32 v71, 1.0, v71
	v_rcp_f32_e32 v71, v71
	v_pk_mul_f32 v[60:61], v[214:215], v[60:61]
	v_mul_f32_e32 v63, v63, v70
	v_mul_f32_e32 v63, v85, v63
	v_mul_f32_e32 v64, v64, v71
	v_pk_mul_f32 v[58:59], v[210:211], v[58:59]
	v_mul_f32_e32 v65, v84, v65
	v_cvt_pk_bf16_f32 v100, v65, v62
	v_mul_f32_e32 v64, v86, v64
	v_cvt_pk_bf16_f32 v101, v63, v64
	s_waitcnt lgkmcnt(0)
	global_store_dwordx4 v[122:123], v[98:101], off
	ds_read_addtid_b32 v84 offset:512
	ds_read_addtid_b32 v85 offset:768
	v_mul_f32_e32 v62, v54, v142
	v_fmac_f32 v62, v6, v134
	v_mul_f32_e32 v63, v55, v143
	v_fmac_f32 v62, v50, v138
	v_fmac_f32 v63, v7, v135
	v_mul_f32_e32 v64, v56, v144
	v_mul_f32_e32 v70, 0xbfb8aa3b, v62
	v_exp_f32_e32 v70, v70
	v_fmac_f32 v63, v51, v139
	v_fmac_f32 v64, v8, v136
	v_mul_f32_e32 v65, v57, v145
	v_add_f32_e32 v70, 1.0, v70
	v_rcp_f32_e32 v70, v70
	v_fmac_f32 v64, v52, v140
	v_fmac_f32 v65, v9, v137
	s_nop 0
	v_mul_f32_e32 v62, v62, v70
	v_mul_f32_e32 v70, 0xbfb8aa3b, v63
	v_exp_f32_e32 v70, v70
	v_mul_f32_e32 v62, v82, v62
	v_fmac_f32 v65, v53, v141
	v_add_f32_e32 v70, 1.0, v70
	v_rcp_f32_e32 v70, v70
	s_nop 0
	v_mul_f32_e32 v63, v63, v70
	v_mul_f32_e32 v63, v81, v63
	v_cvt_pk_bf16_f32 v86, v62, v63
	v_mul_f32_e32 v63, 0xbfb8aa3b, v64
	v_exp_f32_e32 v63, v63
	s_nop 0
	v_add_f32_e32 v63, 1.0, v63
	v_rcp_f32_e32 v63, v63
	s_nop 0
	v_mul_f32_e32 v63, v64, v63
	v_mul_f32_e32 v64, 0xbfb8aa3b, v65
	v_exp_f32_e32 v64, v64
	v_mul_f32_e32 v63, v80, v63
	v_add_f32_e32 v64, 1.0, v64
	v_rcp_f32_e32 v64, v64
	s_nop 0
	v_mul_f32_e32 v64, v65, v64
	v_mul_f32_e32 v64, v79, v64
	v_cvt_pk_bf16_f32 v87, v63, v64
	s_waitcnt lgkmcnt(0)
	global_store_dwordx4 v[124:125], v[84:87], off
	ds_read_addtid_b32 v70 offset:8192
	ds_read_addtid_b32 v71 offset:8448
	v_mul_f32_e32 v62, v50, v142
	v_fmac_f32 v62, v54, v134
	v_mul_f32_e32 v54, v51, v143
	v_fmac_f32 v54, v55, v135
	v_mul_f32_e32 v55, v52, v144
	v_fmac_f32 v55, v56, v136
	v_mul_f32_e32 v56, v53, v145
	v_fmac_f32 v62, v46, v138
	v_fmac_f32 v56, v57, v137
	v_fmac_f32 v54, v47, v139
	v_fmac_f32 v55, v48, v140
	s_nop 0
	v_mul_f32_e32 v57, 0xbfb8aa3b, v62
	v_exp_f32_e32 v57, v57
	v_fmac_f32 v56, v49, v141
	s_nop 0
	v_add_f32_e32 v57, 1.0, v57
	v_rcp_f32_e32 v57, v57
	s_nop 0
	v_mul_f32_e32 v57, v62, v57
	v_mul_f32_e32 v62, 0xbfb8aa3b, v54
	v_exp_f32_e32 v62, v62
	v_mul_f32_e32 v57, v77, v57
	v_add_f32_e32 v62, 1.0, v62
	v_rcp_f32_e32 v62, v62
	s_nop 0
	v_mul_f32_e32 v54, v54, v62
	v_mul_f32_e32 v54, v76, v54
	v_cvt_pk_bf16_f32 v72, v57, v54
	v_mul_f32_e32 v57, 0xbfb8aa3b, v55
	v_exp_f32_e32 v57, v57
	s_nop 0
	v_add_f32_e32 v57, 1.0, v57
	v_rcp_f32_e32 v57, v57
	s_nop 0
	v_mul_f32_e32 v55, v55, v57
	v_mul_f32_e32 v57, 0xbfb8aa3b, v56
	v_exp_f32_e32 v57, v57
	v_mul_f32_e32 v55, v75, v55
	v_add_f32_e32 v57, 1.0, v57
	v_rcp_f32_e32 v57, v57
	s_nop 0
	v_mul_f32_e32 v56, v56, v57
	v_mul_f32_e32 v56, v74, v56
	v_cvt_pk_bf16_f32 v73, v55, v56
	s_waitcnt lgkmcnt(0)
	global_store_dwordx4 v[118:119], v[70:73], off
	ds_read_addtid_b32 v54 offset:8704
	ds_read_addtid_b32 v55 offset:8960
	v_mul_f32_e32 v46, v142, v46
	v_fmac_f32 v46, v50, v134
	v_mul_f32_e32 v47, v143, v47
	v_fmac_f32_dpp v46, v6, v138 row_shl:1 row_mask:0xf bank_mask:0xf
	v_fmac_f32 v47, v51, v135
	v_mul_f32_e32 v48, v144, v48
	v_fmac_f32_e32 v46, v138, v58
	v_fmac_f32_dpp v47, v7, v139 row_shl:1 row_mask:0xf bank_mask:0xf
	v_mul_f32_e32 v50, 0xbfb8aa3b, v46
	v_fmac_f32_e32 v47, v139, v59
	v_exp_f32_e32 v50, v50
	v_mul_f32_e32 v51, 0xbfb8aa3b, v47
	v_exp_f32_e32 v51, v51
	v_fmac_f32 v48, v52, v136
	v_add_f32_e32 v50, 1.0, v50
	v_rcp_f32_e32 v50, v50
	v_add_f32_e32 v51, 1.0, v51
	v_mul_f32_e32 v49, v145, v49
	v_rcp_f32_e32 v51, v51
	v_fmac_f32_dpp v48, v8, v140 row_shl:1 row_mask:0xf bank_mask:0xf
	v_fmac_f32 v49, v53, v137
	v_mul_f32_e32 v46, v46, v50
	v_fmac_f32_e32 v48, v140, v60
	v_fmac_f32_dpp v49, v9, v141 row_shl:1 row_mask:0xf bank_mask:0xf
	v_mul_f32_e32 v50, 0xbfb8aa3b, v48
	v_fmac_f32_e32 v49, v141, v61
	v_mul_f32_e32 v47, v47, v51
	v_exp_f32_e32 v50, v50
	v_mul_f32_e32 v51, 0xbfb8aa3b, v49
	v_exp_f32_e32 v51, v51
	v_mul_f32_e32 v46, v68, v46
	v_add_f32_e32 v50, 1.0, v50
	v_rcp_f32_e32 v50, v50
	v_add_f32_e32 v51, 1.0, v51
	v_rcp_f32_e32 v51, v51
	v_mul_f32_e32 v47, v66, v47
	v_cvt_pk_bf16_f32 v56, v46, v47
	v_mul_f32_e32 v47, v48, v50
	v_mul_f32_e32 v47, v67, v47
	v_mul_f32_e32 v48, v49, v51
	v_mul_f32_e32 v48, v69, v48
	v_cvt_pk_bf16_f32 v57, v47, v48
	s_and_saveexec_b64 s[8:9], s[76:77]
	s_cbranch_execz .LBB0_957
	v_mov_b64_e32 v[48:49], s[42:43]
	v_mad_i64_i32 v[48:49], s[0:1], v120, s21, v[48:49]
	v_lshl_add_u64 v[48:49], v[4:5], 1, v[48:49]
	s_waitcnt lgkmcnt(0)
	global_store_dwordx4 v[48:49], v[54:57], off

.LBB0_965:
	v_mul_f32_e32 v41, v142, v14
	s_waitcnt lgkmcnt(0)
	ds_read_addtid_b32 v62 offset:16384
	ds_read_addtid_b32 v63 offset:16640
	v_pk_mul_f32 v[34:35], v[208:209], v[34:35]
	v_fmac_f32_dpp v41, v18, v134 row_shr:1 row_mask:0xf bank_mask:0xf
	v_pk_mul_f32 v[44:45], v[214:215], v[48:49]
	v_fmac_f32_e32 v41, v134, v34
	v_mul_f32_e32 v34, v143, v15
	v_fmac_f32_dpp v34, v19, v135 row_shr:1 row_mask:0xf bank_mask:0xf
	v_fmac_f32_e32 v39, v152, v44
	v_fmac_f32 v41, v26, v138
	v_fmac_f32_e32 v34, v135, v35
	v_mul_f32_e32 v44, 0xbfb8aa3b, v41
	v_fmac_f32_e32 v40, v153, v45
	v_fmac_f32 v34, v27, v139
	v_mul_f32_e32 v35, v144, v16
	v_exp_f32_e32 v44, v44
	v_mul_f32_e32 v45, 0xbfb8aa3b, v34
	v_pk_mul_f32 v[36:37], v[212:213], v[36:37]
	v_fmac_f32_dpp v35, v20, v136 row_shr:1 row_mask:0xf bank_mask:0xf
	v_exp_f32_e32 v45, v45
	v_fmac_f32_e32 v35, v136, v36
	v_mul_f32_e32 v36, v145, v17
	v_fmac_f32_dpp v36, v21, v137 row_shr:1 row_mask:0xf bank_mask:0xf
	v_fmac_f32 v35, v28, v140
	v_pk_mul_f32 v[46:47], v[210:211], v[46:47]
	v_fmac_f32_e32 v36, v137, v37
	v_add_f32_e32 v37, 1.0, v44
	v_rcp_f32_e32 v37, v37
	v_add_f32_e32 v44, 1.0, v45
	v_rcp_f32_e32 v44, v44
	v_fmac_f32 v36, v29, v141
	v_mul_f32_e32 v37, v41, v37
	v_mul_f32_e32 v41, 0xbfb8aa3b, v35
	v_mul_f32_e32 v34, v34, v44
	v_exp_f32_e32 v41, v41
	v_mul_f32_e32 v44, 0xbfb8aa3b, v36
	v_exp_f32_e32 v44, v44
	v_mul_f32_e32 v34, v58, v34
	v_add_f32_e32 v41, 1.0, v41
	v_rcp_f32_e32 v41, v41
	v_add_f32_e32 v44, 1.0, v44
	v_rcp_f32_e32 v44, v44
	v_fmac_f32_e32 v42, v150, v46
	v_mul_f32_e32 v35, v35, v41
	v_mul_f32_e32 v35, v59, v35
	v_mul_f32_e32 v36, v36, v44
	v_fmac_f32_e32 v38, v151, v47
	v_pk_mul_f32 v[32:33], v[214:215], v[32:33]
	v_pk_mul_f32 v[30:31], v[210:211], v[30:31]
	v_mul_f32_e32 v37, v57, v37
	v_cvt_pk_bf16_f32 v64, v37, v34
	v_mul_f32_e32 v36, v60, v36
	v_cvt_pk_bf16_f32 v65, v35, v36
	s_waitcnt lgkmcnt(0)
	global_store_dwordx4 v[94:95], v[62:65], off
	ds_read_addtid_b32 v44 offset:16896
	ds_read_addtid_b32 v45 offset:17152
	v_mul_f32_e32 v34, v26, v142
	v_fmac_f32 v34, v14, v134
	v_mul_f32_e32 v35, v27, v143
	v_fmac_f32 v34, v22, v138
	v_fmac_f32 v35, v15, v135
	v_mul_f32_e32 v36, v28, v144
	v_mul_f32_e32 v41, 0xbfb8aa3b, v34
	v_exp_f32_e32 v41, v41
	v_fmac_f32 v35, v23, v139
	v_fmac_f32 v36, v16, v136
	v_mul_f32_e32 v37, v29, v145
	v_add_f32_e32 v41, 1.0, v41
	v_rcp_f32_e32 v41, v41
	v_fmac_f32 v36, v24, v140
	v_fmac_f32 v37, v17, v137
	s_nop 0
	v_mul_f32_e32 v34, v34, v41
	v_mul_f32_e32 v41, 0xbfb8aa3b, v35
	v_exp_f32_e32 v41, v41
	v_mul_f32_e32 v34, v56, v34
	v_fmac_f32 v37, v25, v141
	v_add_f32_e32 v41, 1.0, v41
	v_rcp_f32_e32 v41, v41
	s_nop 0
	v_mul_f32_e32 v35, v35, v41
	v_mul_f32_e32 v35, v55, v35
	v_cvt_pk_bf16_f32 v46, v34, v35
	v_mul_f32_e32 v35, 0xbfb8aa3b, v36
	v_exp_f32_e32 v35, v35
	s_nop 0
	v_add_f32_e32 v35, 1.0, v35
	v_rcp_f32_e32 v35, v35
	s_nop 0
	v_mul_f32_e32 v35, v36, v35
	v_mul_f32_e32 v36, 0xbfb8aa3b, v37
	v_exp_f32_e32 v36, v36
	v_mul_f32_e32 v35, v54, v35
	v_add_f32_e32 v36, 1.0, v36
	v_rcp_f32_e32 v36, v36
	s_nop 0
	v_mul_f32_e32 v36, v37, v36
	v_mul_f32_e32 v36, v53, v36
	v_cvt_pk_bf16_f32 v47, v35, v36
	s_waitcnt lgkmcnt(0)
	global_store_dwordx4 v[96:97], v[44:47], off
	ds_read_addtid_b32 v44 offset:24576
	ds_read_addtid_b32 v45 offset:24832
	v_mul_f32_e32 v34, v22, v142
	v_fmac_f32 v34, v26, v134
	v_mul_f32_e32 v26, v23, v143
	v_fmac_f32 v26, v27, v135
	v_mul_f32_e32 v27, v24, v144
	v_fmac_f32 v27, v28, v136
	v_mul_f32_e32 v28, v25, v145
	v_fmac_f32 v34, v18, v138
	v_fmac_f32 v28, v29, v137
	v_fmac_f32 v26, v19, v139
	v_fmac_f32 v27, v20, v140
	s_nop 0
	v_mul_f32_e32 v29, 0xbfb8aa3b, v34
	v_exp_f32_e32 v29, v29
	v_fmac_f32 v28, v21, v141
	s_nop 0
	v_add_f32_e32 v29, 1.0, v29
	v_rcp_f32_e32 v29, v29
	s_nop 0
	v_mul_f32_e32 v29, v34, v29
	v_mul_f32_e32 v34, 0xbfb8aa3b, v26
	v_exp_f32_e32 v34, v34
	v_mul_f32_e32 v29, v52, v29
	v_add_f32_e32 v34, 1.0, v34
	v_rcp_f32_e32 v34, v34
	s_nop 0
	v_mul_f32_e32 v26, v26, v34
	v_mul_f32_e32 v26, v51, v26
	v_cvt_pk_bf16_f32 v46, v29, v26
	v_mul_f32_e32 v29, 0xbfb8aa3b, v27
	v_exp_f32_e32 v29, v29
	s_nop 0
	v_add_f32_e32 v29, 1.0, v29
	v_rcp_f32_e32 v29, v29
	s_nop 0
	v_mul_f32_e32 v27, v27, v29
	v_mul_f32_e32 v29, 0xbfb8aa3b, v28
	v_exp_f32_e32 v29, v29
	v_mul_f32_e32 v27, v50, v27
	v_add_f32_e32 v29, 1.0, v29
	v_rcp_f32_e32 v29, v29
	s_nop 0
	v_mul_f32_e32 v28, v28, v29
	v_mul_f32_e32 v28, v43, v28
	v_cvt_pk_bf16_f32 v47, v27, v28
	s_waitcnt lgkmcnt(0)
	global_store_dwordx4 v[90:91], v[44:47], off
	ds_read_addtid_b32 v34 offset:25088
	ds_read_addtid_b32 v35 offset:25344
	v_mul_f32_e32 v18, v142, v18
	v_fmac_f32 v18, v22, v134
	s_nop 0
	v_fmac_f32_dpp v18, v14, v138 row_shl:1 row_mask:0xf bank_mask:0xf
	v_mul_f32_e32 v14, v143, v19
	v_fmac_f32 v14, v23, v135
	v_fmac_f32_e32 v18, v138, v30
	v_fmac_f32_dpp v14, v15, v139 row_shl:1 row_mask:0xf bank_mask:0xf
	v_mul_f32_e32 v19, 0xbfb8aa3b, v18
	v_fmac_f32_e32 v14, v139, v31
	v_mul_f32_e32 v15, v144, v20
	v_exp_f32_e32 v19, v19
	v_mul_f32_e32 v20, 0xbfb8aa3b, v14
	v_fmac_f32 v15, v24, v136
	v_exp_f32_e32 v20, v20
	v_fmac_f32_dpp v15, v16, v140 row_shl:1 row_mask:0xf bank_mask:0xf
	v_mul_f32_e32 v16, v145, v21
	v_fmac_f32 v16, v25, v137
	v_fmac_f32_e32 v15, v140, v32
	v_fmac_f32_dpp v16, v17, v141 row_shl:1 row_mask:0xf bank_mask:0xf
	v_add_f32_e32 v17, 1.0, v19
	v_rcp_f32_e32 v17, v17
	v_add_f32_e32 v19, 1.0, v20
	v_rcp_f32_e32 v19, v19
	v_fmac_f32_e32 v16, v141, v33
	v_mul_f32_e32 v17, v18, v17
	v_mul_f32_e32 v18, 0xbfb8aa3b, v15
	v_mul_f32_e32 v14, v14, v19
	v_exp_f32_e32 v18, v18
	v_mul_f32_e32 v19, 0xbfb8aa3b, v16
	v_exp_f32_e32 v19, v19
	v_mul_f32_e32 v14, v38, v14
	v_add_f32_e32 v18, 1.0, v18
	v_rcp_f32_e32 v18, v18
	v_add_f32_e32 v19, 1.0, v19
	v_rcp_f32_e32 v19, v19
	v_mul_f32_e32 v17, v42, v17
	v_mul_f32_e32 v15, v15, v18
	v_mul_f32_e32 v15, v39, v15
	v_mul_f32_e32 v16, v16, v19
	v_cvt_pk_bf16_f32 v36, v17, v14
	v_mul_f32_e32 v16, v40, v16
	v_cvt_pk_bf16_f32 v37, v15, v16
	s_and_saveexec_b64 s[8:9], s[70:71]
	s_cbranch_execz .LBB0_967
	v_mov_b64_e32 v[16:17], s[42:43]
	v_mad_i64_i32 v[16:17], s[0:1], v78, s21, v[16:17]
	v_lshl_add_u64 v[16:17], v[4:5], 1, v[16:17]
	s_waitcnt lgkmcnt(0)
	global_store_dwordx4 v[16:17], v[34:37], off

.LBB0_1422:
	s_or_b64 exec, exec, s[8:9]
	s_and_b32 s1, s15, 1
	s_bitcmp1_b32 s15, 0
	s_cselect_b64 s[66:67], -1, 0
	s_lshl_b32 s0, s0, 11
	s_xor_b32 s0, s0, 0x800
	s_add_i32 s72, s0, 0
	s_add_i32 s72, s72, 0x22400
	s_and_b32 s0, s15, 16
	s_bitcmp1_b32 s95, 0
	s_cselect_b32 s3, 0xc00, 0
	s_add_i32 s15, s3, 0
	s_add_i32 s15, s15, 0x23400
	v_or_b32_e32 v2, s1, v231
	s_cmp_eq_u32 s0, 0
	v_cmp_eq_u32_e64 s[8:9], 0, v2
	s_cbranch_scc1 .LBB0_1518
	s_waitcnt lgkmcnt(0)
	s_barrier
	s_mov_b32 s98, 0xffff0000
	s_mov_b32 s99, 0xffff0000
	s_mov_b32 s100, 0xffff
	s_mov_b32 s101, 0xffff
	v_lshl_add_u32 v4, v206, 2, s15
	ds_read_b128 v[146:149], v4 offset:256
	ds_read_b128 v[134:137], v4 offset:768
	ds_read_b128 v[154:157], v4 offset:1280
	ds_read_b128 v[142:145], v4 offset:1792
	ds_read_b128 v[150:153], v4 offset:2304
	ds_read_b128 v[138:141], v4 offset:2816
	s_andn2_b64 vcc, exec, s[68:69]
	s_add_i32 s73, s72, 0x400
	s_cbranch_vccnz .LBB0_1447
	s_waitcnt lgkmcnt(0)
	ds_read_b128 v[174:177], v4
	ds_read_b128 v[162:165], v4 offset:512
	ds_read_b128 v[178:181], v4 offset:1024
	ds_read_b128 v[166:169], v4 offset:1536
	ds_read_b128 v[170:173], v4 offset:2048
	ds_read_b128 v[158:161], v4 offset:2560
	s_and_b64 s[68:69], s[50:51], s[66:67]
	v_mov_b32_e32 v182, 0
	s_and_b64 vcc, exec, s[68:69]
	v_mov_b32_e32 v186, 0
	v_mov_b32_e32 v187, 0
	v_mov_b32_e32 v188, 0
	v_mov_b32_e32 v189, 0
	s_cbranch_vccnz .LBB0_1426
	s_and_b64 s[0:1], s[50:51], exec
	s_cselect_b32 s0, s73, s88
	v_lshl_add_u32 v4, v228, 2, s0
	ds_read_b128 v[186:189], v4

.LBB0_1432:
	v_pk_mul_f32 v[4:5], v[214:215], v[184:185]
	s_waitcnt lgkmcnt(0)
	v_pk_mul_f32 v[184:185], v[210:211], v[186:187]
	v_mul_f32_e32 v186, v10, v166
	v_pk_mul_f32 v[190:191], v[208:209], v[190:191]
	v_fmac_f32_dpp v186, v58, v162 row_shr:1 row_mask:0xf bank_mask:0xf
	v_mul_f32_e32 v187, v11, v167
	v_pk_mul_f32 v[182:183], v[210:211], v[182:183]
	v_fmac_f32_e32 v186, v162, v190
	v_fmac_f32_dpp v187, v59, v163 row_shr:1 row_mask:0xf bank_mask:0xf
	v_fmac_f32_e32 v221, v170, v182
	v_fmac_f32_e32 v220, v171, v183
	v_pk_mul_f32 v[182:183], v[214:215], v[188:189]
	v_fmac_f32 v186, v66, v158
	v_fmac_f32_e32 v187, v163, v191
	v_mul_f32_e32 v188, 0xbfb8aa3b, v186
	v_fmac_f32 v187, v67, v159
	v_exp_f32_e32 v188, v188
	v_mul_f32_e32 v191, 0xbfb8aa3b, v187
	v_exp_f32_e32 v191, v191
	v_mul_f32_e32 v189, v12, v168
	v_add_f32_e32 v188, 1.0, v188
	v_rcp_f32_e32 v188, v188
	v_add_f32_e32 v191, 1.0, v191
	v_rcp_f32_e32 v191, v191
	v_pk_mul_f32 v[192:193], v[212:213], v[192:193]
	v_fmac_f32_dpp v189, v60, v164 row_shr:1 row_mask:0xf bank_mask:0xf
	v_mul_f32_e32 v190, v13, v169
	v_fmac_f32_e32 v189, v164, v192
	v_fmac_f32_dpp v190, v61, v165 row_shr:1 row_mask:0xf bank_mask:0xf
	v_fmac_f32 v189, v68, v160
	v_mul_f32_e32 v186, v186, v188
	v_fmac_f32_e32 v190, v165, v193
	v_mul_f32_e32 v188, 0xbfb8aa3b, v189
	v_fmac_f32 v190, v69, v161
	v_mul_f32_e32 v187, v187, v191
	v_exp_f32_e32 v188, v188
	v_mul_f32_e32 v191, 0xbfb8aa3b, v190
	v_exp_f32_e32 v191, v191
	v_mul_f32_e32 v186, v195, v186
	v_add_f32_e32 v188, 1.0, v188
	v_rcp_f32_e32 v192, v188
	v_add_f32_e32 v188, 1.0, v191
	v_rcp_f32_e32 v191, v188
	v_mul_f32_e32 v187, v194, v187
	v_cvt_pk_bf16_f32 v122, v186, v187
	v_mul_f32_e32 v186, v189, v192
	v_mul_f32_e32 v187, v190, v191
	v_fmac_f32_e32 v197, v172, v4
	v_lshl_or_b32 v4, s14, 7, v206
	v_mul_f32_e32 v186, v249, v186
	v_mul_f32_e32 v187, v250, v187
	s_lshl_b32 s70, s94, 8
	v_fmac_f32_e32 v196, v173, v5
	v_ashrrev_i32_e32 v5, 31, v4
	v_cvt_pk_bf16_f32 v123, v186, v187
	v_add_u32_e32 v190, s70, v230
	v_mov_b64_e32 v[186:187], s[42:43]
	v_mad_i64_i32 v[190:191], s[0:1], v190, s90, v[186:187]
	v_lshlrev_b64 v[194:195], 1, v[4:5]
	v_lshl_add_u64 v[190:191], v[190:191], 0, v[194:195]
	v_mul_f32_e32 v188, v66, v166
	v_fmac_f32 v188, v10, v162
	v_mul_f32_e32 v189, v67, v167
	v_fmac_f32 v188, v62, v158
	v_fmac_f32 v189, v11, v163
	v_mul_f32_e32 v190, v68, v168
	v_mul_f32_e32 v192, 0xbfb8aa3b, v188
	v_exp_f32_e32 v192, v192
	v_fmac_f32 v189, v63, v159
	v_fmac_f32 v190, v12, v164
	v_mul_f32_e32 v191, v69, v169
	v_add_f32_e32 v192, 1.0, v192
	v_rcp_f32_e32 v192, v192
	v_fmac_f32 v190, v64, v160
	v_fmac_f32 v191, v13, v165
	s_nop 0
	v_mul_f32_e32 v188, v188, v192
	v_mul_f32_e32 v192, 0xbfb8aa3b, v189
	v_exp_f32_e32 v192, v192
	v_mul_f32_e32 v188, v248, v188
	v_fmac_f32 v191, v65, v161
	v_add_f32_e32 v192, 1.0, v192
	v_rcp_f32_e32 v192, v192
	s_nop 0
	v_mul_f32_e32 v189, v189, v192
	v_mul_f32_e32 v189, v247, v189
	v_cvt_pk_bf16_f32 v124, v188, v189
	v_mul_f32_e32 v189, 0xbfb8aa3b, v190
	v_exp_f32_e32 v189, v189
	s_nop 0
	v_add_f32_e32 v189, 1.0, v189
	v_rcp_f32_e32 v189, v189
	s_nop 0
	v_mul_f32_e32 v189, v190, v189
	v_mul_f32_e32 v190, 0xbfb8aa3b, v191
	v_exp_f32_e32 v190, v190
	v_mul_f32_e32 v189, v246, v189
	v_add_f32_e32 v190, 1.0, v190
	v_rcp_f32_e32 v190, v190
	s_nop 0
	v_mul_f32_e32 v190, v191, v190
	v_mul_f32_e32 v190, v245, v190
	v_cvt_pk_bf16_f32 v125, v189, v190
	s_nop 1
	v_permlane16_swap_b32 v122, v124
	v_permlane16_swap_b32 v123, v125
	v_cndmask_b32_e64 v190, v230, v232, s[98:99]
	v_add_u32_e32 v190, s70, v190
	v_mad_i64_i32 v[190:191], s[0:1], v190, s90, v[186:187]
	v_lshl_add_u64 v[190:191], v[190:191], 0, v[194:195]
	v_cndmask_b32_e64 v188, 0, -8, s[98:99]
	v_ashrrev_i32_e32 v189, 31, v188
	v_lshl_add_u64 v[190:191], v[190:191], 0, v[188:189]
	global_store_dwordx4 v[190:191], v[122:125], off
	v_mul_f32_e32 v188, v62, v166
	v_fmac_f32 v188, v66, v162
	v_mul_f32_e32 v189, v63, v167
	v_fmac_f32 v188, v58, v158
	v_fmac_f32 v189, v67, v163
	v_mul_f32_e32 v190, v64, v168
	v_mul_f32_e32 v192, 0xbfb8aa3b, v188
	v_exp_f32_e32 v192, v192
	v_fmac_f32 v189, v59, v159
	v_fmac_f32 v190, v68, v164
	v_mul_f32_e32 v191, v65, v169
	v_add_f32_e32 v192, 1.0, v192
	v_rcp_f32_e32 v192, v192
	v_fmac_f32 v190, v60, v160
	v_fmac_f32 v191, v69, v165
	s_nop 0
	v_mul_f32_e32 v188, v188, v192
	v_mul_f32_e32 v192, 0xbfb8aa3b, v189
	v_exp_f32_e32 v192, v192
	v_mul_f32_e32 v188, v225, v188
	v_fmac_f32 v191, v61, v161
	v_add_f32_e32 v192, 1.0, v192
	v_rcp_f32_e32 v192, v192
	s_nop 0
	v_mul_f32_e32 v189, v189, v192
	v_mul_f32_e32 v189, v224, v189
	v_cvt_pk_bf16_f32 v66, v188, v189
	v_mul_f32_e32 v189, 0xbfb8aa3b, v190
	v_exp_f32_e32 v189, v189
	s_nop 0
	v_add_f32_e32 v189, 1.0, v189
	v_rcp_f32_e32 v189, v189
	s_nop 0
	v_mul_f32_e32 v189, v190, v189
	v_mul_f32_e32 v190, 0xbfb8aa3b, v191
	v_exp_f32_e32 v190, v190
	v_mul_f32_e32 v189, v223, v189
	v_add_f32_e32 v190, 1.0, v190
	v_rcp_f32_e32 v190, v190
	s_nop 0
	v_mul_f32_e32 v190, v191, v190
	v_mul_f32_e32 v190, v222, v190
	v_cvt_pk_bf16_f32 v67, v189, v190
	v_add_u32_e32 v190, s70, v233
	v_mad_i64_i32 v[186:187], s[0:1], v190, s90, v[186:187]
	v_lshl_add_u64 v[186:187], v[186:187], 0, v[194:195]
	v_mul_f32_e32 v186, v58, v166
	v_fmac_f32 v186, v62, v162
	v_mul_f32_e32 v187, v61, v169
	v_fmac_f32_dpp v186, v10, v158 row_shl:1 row_mask:0xf bank_mask:0xf
	v_fmac_f32 v187, v65, v165
	s_or_b64 s[0:1], s[16:17], s[4:5]
	v_fmac_f32_e32 v186, v158, v184
	v_mul_f32_e32 v184, v59, v167
	v_fmac_f32 v184, v63, v163
	v_fmac_f32_dpp v187, v13, v161 row_shl:1 row_mask:0xf bank_mask:0xf
	s_nop 0
	v_fmac_f32_dpp v184, v11, v159 row_shl:1 row_mask:0xf bank_mask:0xf
	v_fmac_f32_e32 v187, v161, v183
	v_fmac_f32_e32 v184, v159, v185
	v_mul_f32_e32 v185, v60, v168
	v_fmac_f32 v185, v64, v164
	v_mul_f32_e32 v183, 0xbfb8aa3b, v184
	v_fmac_f32_dpp v185, v12, v160 row_shl:1 row_mask:0xf bank_mask:0xf
	v_exp_f32_e32 v183, v183
	v_fmac_f32_e32 v185, v160, v182
	v_mul_f32_e32 v182, 0xbfb8aa3b, v186
	v_exp_f32_e32 v182, v182
	v_add_f32_e32 v183, 1.0, v183
	v_rcp_f32_e32 v183, v183
	v_add_f32_e32 v182, 1.0, v182
	v_rcp_f32_e32 v182, v182
	v_mul_f32_e32 v183, v184, v183
	v_mul_f32_e32 v183, v220, v183
	v_mul_f32_e32 v184, 0xbfb8aa3b, v187
	v_mul_f32_e32 v182, v186, v182
	v_mul_f32_e32 v182, v221, v182
	v_cvt_pk_bf16_f32 v68, v182, v183
	v_mul_f32_e32 v183, 0xbfb8aa3b, v185
	v_exp_f32_e32 v183, v183
	v_exp_f32_e32 v184, v184
	v_add_f32_e32 v183, 1.0, v183
	v_rcp_f32_e32 v183, v183
	v_add_f32_e32 v184, 1.0, v184
	v_rcp_f32_e32 v184, v184
	v_mul_f32_e32 v183, v185, v183
	v_mul_f32_e32 v183, v197, v183
	v_mul_f32_e32 v184, v187, v184
	v_mul_f32_e32 v184, v196, v184
	v_cvt_pk_bf16_f32 v69, v183, v184
	s_nop 1
	v_permlane16_swap_b32 v66, v68
	v_permlane16_swap_b32 v67, v69
	s_or_b64 s[0:1], s[0:1], s[100:101]
	s_and_saveexec_b64 s[10:11], s[0:1]
	s_cbranch_execz .LBB0_1434
	v_cndmask_b32_e64 v186, v233, v234, s[98:99]
	v_add_u32_e32 v186, s70, v186
	v_mov_b64_e32 v[184:185], s[42:43]
	v_mad_i64_i32 v[184:185], s[0:1], v186, s90, v[184:185]
	v_lshl_add_u64 v[184:185], v[4:5], 1, v[184:185]
	v_cndmask_b32_e64 v182, 0, -8, s[98:99]
	v_ashrrev_i32_e32 v183, 31, v182
	v_lshl_add_u64 v[184:185], v[184:185], 0, v[182:183]
	global_store_dwordx4 v[184:185], v[66:69], off

.LBB0_1442:
	v_pk_mul_f32 v[184:185], v[214:215], v[184:185]
	s_waitcnt lgkmcnt(0)
	v_pk_mul_f32 v[190:191], v[208:209], v[190:191]
	v_fmac_f32_e32 v197, v172, v184
	v_fmac_f32_e32 v196, v173, v185
	v_pk_mul_f32 v[184:185], v[210:211], v[186:187]
	v_mul_f32_e32 v186, v30, v166
	v_fmac_f32_dpp v186, v34, v162 row_shr:1 row_mask:0xf bank_mask:0xf
	v_mul_f32_e32 v187, v31, v167
	v_pk_mul_f32 v[182:183], v[210:211], v[182:183]
	v_fmac_f32_e32 v186, v162, v190
	v_fmac_f32_dpp v187, v35, v163 row_shr:1 row_mask:0xf bank_mask:0xf
	v_fmac_f32_e32 v221, v170, v182
	v_fmac_f32_e32 v220, v171, v183
	v_pk_mul_f32 v[182:183], v[214:215], v[188:189]
	v_fmac_f32 v186, v42, v158
	v_fmac_f32_e32 v187, v163, v191
	v_mul_f32_e32 v188, 0xbfb8aa3b, v186
	v_fmac_f32 v187, v43, v159
	v_exp_f32_e32 v188, v188
	v_mul_f32_e32 v191, 0xbfb8aa3b, v187
	v_exp_f32_e32 v191, v191
	v_mul_f32_e32 v189, v32, v168
	v_add_f32_e32 v188, 1.0, v188
	v_rcp_f32_e32 v188, v188
	v_add_f32_e32 v191, 1.0, v191
	v_rcp_f32_e32 v191, v191
	v_pk_mul_f32 v[192:193], v[212:213], v[192:193]
	v_fmac_f32_dpp v189, v36, v164 row_shr:1 row_mask:0xf bank_mask:0xf
	v_mul_f32_e32 v190, v33, v169
	v_fmac_f32_e32 v189, v164, v192
	v_fmac_f32_dpp v190, v37, v165 row_shr:1 row_mask:0xf bank_mask:0xf
	v_fmac_f32 v189, v44, v160
	v_mul_f32_e32 v186, v186, v188
	v_fmac_f32_e32 v190, v165, v193
	v_mul_f32_e32 v188, 0xbfb8aa3b, v189
	v_fmac_f32 v190, v45, v161
	v_mul_f32_e32 v187, v187, v191
	v_exp_f32_e32 v188, v188
	v_mul_f32_e32 v191, 0xbfb8aa3b, v190
	v_exp_f32_e32 v191, v191
	v_mul_f32_e32 v186, v249, v186
	v_add_f32_e32 v188, 1.0, v188
	v_rcp_f32_e32 v192, v188
	v_add_f32_e32 v188, 1.0, v191
	v_rcp_f32_e32 v191, v188
	v_mul_f32_e32 v187, v250, v187
	v_cvt_pk_bf16_f32 v58, v186, v187
	v_mul_f32_e32 v186, v189, v192
	v_mul_f32_e32 v187, v190, v191
	v_mul_f32_e32 v186, v251, v186
	v_mul_f32_e32 v187, v252, v187
	v_cvt_pk_bf16_f32 v59, v186, v187
	v_add_u32_e32 v190, s70, v235
	v_mov_b64_e32 v[186:187], s[42:43]
	v_mad_i64_i32 v[190:191], s[0:1], v190, s90, v[186:187]
	v_lshl_add_u64 v[190:191], v[190:191], 0, v[194:195]
	v_mul_f32_e32 v188, v42, v166
	v_fmac_f32 v188, v30, v162
	v_mul_f32_e32 v189, v43, v167
	v_fmac_f32 v188, v38, v158
	v_fmac_f32 v189, v31, v163
	v_mul_f32_e32 v190, v44, v168
	v_mul_f32_e32 v192, 0xbfb8aa3b, v188
	v_exp_f32_e32 v192, v192
	v_fmac_f32 v189, v39, v159
	v_fmac_f32 v190, v32, v164
	v_mul_f32_e32 v191, v45, v169
	v_add_f32_e32 v192, 1.0, v192
	v_rcp_f32_e32 v192, v192
	v_fmac_f32 v190, v40, v160
	v_fmac_f32 v191, v33, v165
	s_nop 0
	v_mul_f32_e32 v188, v188, v192
	v_mul_f32_e32 v192, 0xbfb8aa3b, v189
	v_exp_f32_e32 v192, v192
	v_mul_f32_e32 v188, v248, v188
	v_fmac_f32 v191, v41, v161
	v_add_f32_e32 v192, 1.0, v192
	v_rcp_f32_e32 v192, v192
	s_nop 0
	v_mul_f32_e32 v189, v189, v192
	v_mul_f32_e32 v189, v247, v189
	v_cvt_pk_bf16_f32 v60, v188, v189
	v_mul_f32_e32 v189, 0xbfb8aa3b, v190
	v_exp_f32_e32 v189, v189
	s_nop 0
	v_add_f32_e32 v189, 1.0, v189
	v_rcp_f32_e32 v189, v189
	s_nop 0
	v_mul_f32_e32 v189, v190, v189
	v_mul_f32_e32 v190, 0xbfb8aa3b, v191
	v_exp_f32_e32 v190, v190
	v_mul_f32_e32 v189, v246, v189
	v_add_f32_e32 v190, 1.0, v190
	v_rcp_f32_e32 v190, v190
	s_nop 0
	v_mul_f32_e32 v190, v191, v190
	v_mul_f32_e32 v190, v245, v190
	v_cvt_pk_bf16_f32 v61, v189, v190
	s_nop 1
	v_permlane16_swap_b32 v58, v60
	v_permlane16_swap_b32 v59, v61
	v_cndmask_b32_e64 v190, v235, v236, s[98:99]
	v_add_u32_e32 v190, s70, v190
	v_mad_i64_i32 v[190:191], s[0:1], v190, s90, v[186:187]
	v_lshl_add_u64 v[190:191], v[190:191], 0, v[194:195]
	v_cndmask_b32_e64 v188, 0, -8, s[98:99]
	v_ashrrev_i32_e32 v189, 31, v188
	v_lshl_add_u64 v[190:191], v[190:191], 0, v[188:189]
	global_store_dwordx4 v[190:191], v[58:61], off
	v_mul_f32_e32 v188, v38, v166
	v_fmac_f32 v188, v42, v162
	v_mul_f32_e32 v189, v39, v167
	v_fmac_f32 v188, v34, v158
	v_fmac_f32 v189, v43, v163
	v_mul_f32_e32 v190, v40, v168
	v_mul_f32_e32 v192, 0xbfb8aa3b, v188
	v_exp_f32_e32 v192, v192
	v_fmac_f32 v189, v35, v159
	v_fmac_f32 v190, v44, v164
	v_mul_f32_e32 v191, v41, v169
	v_add_f32_e32 v192, 1.0, v192
	v_rcp_f32_e32 v192, v192
	v_fmac_f32 v190, v36, v160
	v_fmac_f32 v191, v45, v165
	s_nop 0
	v_mul_f32_e32 v188, v188, v192
	v_mul_f32_e32 v192, 0xbfb8aa3b, v189
	v_exp_f32_e32 v192, v192
	v_mul_f32_e32 v188, v225, v188
	v_fmac_f32 v191, v37, v161
	v_add_f32_e32 v192, 1.0, v192
	v_rcp_f32_e32 v192, v192
	s_nop 0
	v_mul_f32_e32 v189, v189, v192
	v_mul_f32_e32 v189, v224, v189
	v_cvt_pk_bf16_f32 v42, v188, v189
	v_mul_f32_e32 v189, 0xbfb8aa3b, v190
	v_exp_f32_e32 v189, v189
	s_nop 0
	v_add_f32_e32 v189, 1.0, v189
	v_rcp_f32_e32 v189, v189
	s_nop 0
	v_mul_f32_e32 v189, v190, v189
	v_mul_f32_e32 v190, 0xbfb8aa3b, v191
	v_exp_f32_e32 v190, v190
	v_mul_f32_e32 v189, v223, v189
	v_add_f32_e32 v190, 1.0, v190
	v_rcp_f32_e32 v190, v190
	s_nop 0
	v_mul_f32_e32 v190, v191, v190
	v_mul_f32_e32 v190, v222, v190
	v_cvt_pk_bf16_f32 v43, v189, v190
	v_add_u32_e32 v190, s70, v237
	v_mad_i64_i32 v[186:187], s[0:1], v190, s90, v[186:187]
	v_lshl_add_u64 v[186:187], v[186:187], 0, v[194:195]
	v_mul_f32_e32 v186, v34, v166
	v_fmac_f32 v186, v38, v162
	v_mul_f32_e32 v187, v37, v169
	v_fmac_f32_dpp v186, v30, v158 row_shl:1 row_mask:0xf bank_mask:0xf
	v_fmac_f32 v187, v41, v165
	s_or_b64 s[0:1], s[16:17], s[6:7]
	v_fmac_f32_e32 v186, v158, v184
	v_mul_f32_e32 v184, v35, v167
	v_fmac_f32 v184, v39, v163
	v_fmac_f32_dpp v187, v33, v161 row_shl:1 row_mask:0xf bank_mask:0xf
	s_nop 0
	v_fmac_f32_dpp v184, v31, v159 row_shl:1 row_mask:0xf bank_mask:0xf
	v_fmac_f32_e32 v187, v161, v183
	v_fmac_f32_e32 v184, v159, v185
	v_mul_f32_e32 v185, v36, v168
	v_fmac_f32 v185, v40, v164
	v_mul_f32_e32 v183, 0xbfb8aa3b, v184
	v_fmac_f32_dpp v185, v32, v160 row_shl:1 row_mask:0xf bank_mask:0xf
	v_exp_f32_e32 v183, v183
	v_fmac_f32_e32 v185, v160, v182
	v_mul_f32_e32 v182, 0xbfb8aa3b, v186
	v_exp_f32_e32 v182, v182
	v_add_f32_e32 v183, 1.0, v183
	v_rcp_f32_e32 v183, v183
	v_add_f32_e32 v182, 1.0, v182
	v_rcp_f32_e32 v182, v182
	v_mul_f32_e32 v183, v184, v183
	v_mul_f32_e32 v183, v220, v183
	v_mul_f32_e32 v184, 0xbfb8aa3b, v187
	v_mul_f32_e32 v182, v186, v182
	v_mul_f32_e32 v182, v221, v182
	v_cvt_pk_bf16_f32 v44, v182, v183
	v_mul_f32_e32 v183, 0xbfb8aa3b, v185
	v_exp_f32_e32 v183, v183
	v_exp_f32_e32 v184, v184
	v_add_f32_e32 v183, 1.0, v183
	v_rcp_f32_e32 v183, v183
	v_add_f32_e32 v184, 1.0, v184
	v_rcp_f32_e32 v184, v184
	v_mul_f32_e32 v183, v185, v183
	v_mul_f32_e32 v183, v197, v183
	v_mul_f32_e32 v184, v187, v184
	v_mul_f32_e32 v184, v196, v184
	v_cvt_pk_bf16_f32 v45, v183, v184
	s_nop 1
	v_permlane16_swap_b32 v42, v44
	v_permlane16_swap_b32 v43, v45
	s_or_b64 s[0:1], s[0:1], s[100:101]
	s_and_saveexec_b64 s[10:11], s[0:1]
	s_cbranch_execz .LBB0_1444
	v_cndmask_b32_e64 v186, v237, v238, s[98:99]
	v_add_u32_e32 v186, s70, v186
	v_mov_b64_e32 v[184:185], s[42:43]
	v_mad_i64_i32 v[184:185], s[0:1], v186, s90, v[184:185]
	v_lshl_add_u64 v[184:185], v[4:5], 1, v[184:185]
	v_cndmask_b32_e64 v182, 0, -8, s[98:99]
	v_ashrrev_i32_e32 v183, 31, v182
	v_lshl_add_u64 v[184:185], v[184:185], 0, v[182:183]
	global_store_dwordx4 v[184:185], v[42:45], off

.LBB0_1456:
	v_pk_mul_f32 v[160:161], v[214:215], v[160:161]
	s_waitcnt lgkmcnt(0)
	v_pk_mul_f32 v[166:167], v[208:209], v[166:167]
	v_fmac_f32_e32 v173, v152, v160
	v_fmac_f32_e32 v172, v153, v161
	v_pk_mul_f32 v[160:161], v[210:211], v[162:163]
	v_mul_f32_e32 v162, v142, v6
	v_fmac_f32_dpp v162, v46, v134 row_shr:1 row_mask:0xf bank_mask:0xf
	v_mul_f32_e32 v163, v143, v7
	v_pk_mul_f32 v[158:159], v[210:211], v[158:159]
	v_fmac_f32_e32 v162, v134, v166
	v_fmac_f32_dpp v163, v47, v135 row_shr:1 row_mask:0xf bank_mask:0xf
	v_fmac_f32_e32 v175, v150, v158
	v_fmac_f32_e32 v174, v151, v159
	v_pk_mul_f32 v[158:159], v[214:215], v[164:165]
	v_fmac_f32 v162, v54, v138
	v_fmac_f32_e32 v163, v135, v167
	v_mul_f32_e32 v164, 0xbfb8aa3b, v162
	v_fmac_f32 v163, v55, v139
	v_exp_f32_e32 v164, v164
	v_mul_f32_e32 v167, 0xbfb8aa3b, v163
	v_exp_f32_e32 v167, v167
	v_mul_f32_e32 v165, v144, v8
	v_add_f32_e32 v164, 1.0, v164
	v_rcp_f32_e32 v164, v164
	v_add_f32_e32 v167, 1.0, v167
	v_rcp_f32_e32 v167, v167
	v_pk_mul_f32 v[168:169], v[212:213], v[168:169]
	v_fmac_f32_dpp v165, v48, v136 row_shr:1 row_mask:0xf bank_mask:0xf
	v_mul_f32_e32 v166, v145, v9
	v_fmac_f32_e32 v165, v136, v168
	v_fmac_f32_dpp v166, v49, v137 row_shr:1 row_mask:0xf bank_mask:0xf
	v_mul_f32_e32 v162, v162, v164
	v_fmac_f32 v165, v56, v140
	v_fmac_f32_e32 v166, v137, v169
	v_mul_f32_e32 v5, v5, v162
	v_mul_f32_e32 v162, v163, v167
	v_mul_f32_e32 v163, 0xbfb8aa3b, v165
	v_fmac_f32 v166, v57, v141
	v_exp_f32_e32 v163, v163
	v_mul_f32_e32 v164, 0xbfb8aa3b, v166
	v_exp_f32_e32 v164, v164
	v_mul_f32_e32 v4, v4, v162
	v_add_f32_e32 v162, 1.0, v163
	v_rcp_f32_e32 v162, v162
	v_add_f32_e32 v163, 1.0, v164
	v_rcp_f32_e32 v163, v163
	v_cvt_pk_bf16_f32 v10, v5, v4
	v_mul_f32_e32 v4, v165, v162
	v_mul_f32_e32 v4, v170, v4
	v_mul_f32_e32 v5, v166, v163
	s_lshl_b32 s74, s94, 8
	v_mul_f32_e32 v5, v171, v5
	v_cvt_pk_bf16_f32 v11, v4, v5
	v_add_u32_e32 v4, s74, v230
	v_mov_b64_e32 v[162:163], s[42:43]
	s_lshl_b32 s75, s14, 7
	v_mad_i64_i32 v[166:167], s[0:1], v4, s90, v[162:163]
	s_ashr_i32 s0, s75, 31
	s_nop 0
	v_mov_b32_e32 v5, s0
	v_or_b32_e32 v4, s75, v206
	v_lshlrev_b64 v[170:171], 1, v[4:5]
	v_lshl_add_u64 v[166:167], v[166:167], 0, v[170:171]
	v_mul_f32_e32 v164, v54, v142
	v_fmac_f32 v164, v6, v134
	v_mul_f32_e32 v165, v55, v143
	v_fmac_f32 v164, v50, v138
	v_fmac_f32 v165, v7, v135
	v_mul_f32_e32 v166, v56, v144
	v_mul_f32_e32 v168, 0xbfb8aa3b, v164
	v_exp_f32_e32 v168, v168
	v_fmac_f32 v165, v51, v139
	v_fmac_f32 v166, v8, v136
	v_mul_f32_e32 v167, v57, v145
	v_add_f32_e32 v168, 1.0, v168
	v_rcp_f32_e32 v168, v168
	v_fmac_f32 v166, v52, v140
	v_fmac_f32 v167, v9, v137
	s_nop 0
	v_mul_f32_e32 v164, v164, v168
	v_mul_f32_e32 v168, 0xbfb8aa3b, v165
	v_exp_f32_e32 v168, v168
	v_mul_f32_e32 v164, v183, v164
	v_fmac_f32 v167, v53, v141
	v_add_f32_e32 v168, 1.0, v168
	v_rcp_f32_e32 v168, v168
	s_nop 0
	v_mul_f32_e32 v165, v165, v168
	v_mul_f32_e32 v165, v182, v165
	v_cvt_pk_bf16_f32 v12, v164, v165
	v_mul_f32_e32 v165, 0xbfb8aa3b, v166
	v_exp_f32_e32 v165, v165
	s_nop 0
	v_add_f32_e32 v165, 1.0, v165
	v_rcp_f32_e32 v165, v165
	s_nop 0
	v_mul_f32_e32 v165, v166, v165
	v_mul_f32_e32 v166, 0xbfb8aa3b, v167
	v_exp_f32_e32 v166, v166
	v_mul_f32_e32 v165, v181, v165
	v_add_f32_e32 v166, 1.0, v166
	v_rcp_f32_e32 v166, v166
	s_nop 0
	v_mul_f32_e32 v166, v167, v166
	v_mul_f32_e32 v166, v180, v166
	v_cvt_pk_bf16_f32 v13, v165, v166
	s_nop 1
	v_permlane16_swap_b32 v10, v12
	v_permlane16_swap_b32 v11, v13
	v_cndmask_b32_e64 v166, v230, v232, s[98:99]
	v_add_u32_e32 v166, s74, v166
	v_mad_i64_i32 v[166:167], s[0:1], v166, s90, v[162:163]
	v_lshl_add_u64 v[166:167], v[166:167], 0, v[170:171]
	v_cndmask_b32_e64 v164, 0, -8, s[98:99]
	v_ashrrev_i32_e32 v165, 31, v164
	v_lshl_add_u64 v[166:167], v[166:167], 0, v[164:165]
	global_store_dwordx4 v[166:167], v[10:13], off offset:128
	v_mul_f32_e32 v164, v50, v142
	v_fmac_f32 v164, v54, v134
	v_mul_f32_e32 v165, v51, v143
	v_fmac_f32 v164, v46, v138
	v_fmac_f32 v165, v55, v135
	v_mul_f32_e32 v166, v52, v144
	v_mul_f32_e32 v168, 0xbfb8aa3b, v164
	v_exp_f32_e32 v168, v168
	v_fmac_f32 v165, v47, v139
	v_fmac_f32 v166, v56, v136
	v_mul_f32_e32 v167, v53, v145
	v_add_f32_e32 v168, 1.0, v168
	v_rcp_f32_e32 v168, v168
	v_fmac_f32 v166, v48, v140
	v_fmac_f32 v167, v57, v137
	s_nop 0
	v_mul_f32_e32 v164, v164, v168
	v_mul_f32_e32 v168, 0xbfb8aa3b, v165
	v_exp_f32_e32 v168, v168
	v_mul_f32_e32 v164, v179, v164
	v_fmac_f32 v167, v49, v141
	v_add_f32_e32 v168, 1.0, v168
	v_rcp_f32_e32 v168, v168
	s_nop 0
	v_mul_f32_e32 v165, v165, v168
	v_mul_f32_e32 v165, v178, v165
	v_cvt_pk_bf16_f32 v10, v164, v165
	v_mul_f32_e32 v165, 0xbfb8aa3b, v166
	v_exp_f32_e32 v165, v165
	s_nop 0
	v_add_f32_e32 v165, 1.0, v165
	v_rcp_f32_e32 v165, v165
	s_nop 0
	v_mul_f32_e32 v165, v166, v165
	v_mul_f32_e32 v166, 0xbfb8aa3b, v167
	v_exp_f32_e32 v166, v166
	v_mul_f32_e32 v165, v177, v165
	v_add_f32_e32 v166, 1.0, v166
	v_rcp_f32_e32 v166, v166
	s_nop 0
	v_mul_f32_e32 v166, v167, v166
	v_mul_f32_e32 v166, v176, v166
	v_cvt_pk_bf16_f32 v11, v165, v166
	v_add_u32_e32 v166, s74, v233
	v_mad_i64_i32 v[162:163], s[0:1], v166, s90, v[162:163]
	v_lshl_add_u64 v[162:163], v[162:163], 0, v[170:171]
	v_mul_f32_e32 v162, v142, v46
	v_fmac_f32 v162, v50, v134
	v_mul_f32_e32 v163, v145, v49
	v_fmac_f32_dpp v162, v6, v138 row_shl:1 row_mask:0xf bank_mask:0xf
	v_fmac_f32 v163, v53, v137
	s_or_b64 s[0:1], s[16:17], s[4:5]
	v_fmac_f32_e32 v162, v138, v160
	v_mul_f32_e32 v160, v143, v47
	v_fmac_f32 v160, v51, v135
	v_fmac_f32_dpp v163, v9, v141 row_shl:1 row_mask:0xf bank_mask:0xf
	s_nop 0
	v_fmac_f32_dpp v160, v7, v139 row_shl:1 row_mask:0xf bank_mask:0xf
	v_fmac_f32_e32 v163, v141, v159
	v_fmac_f32_e32 v160, v139, v161
	v_mul_f32_e32 v161, v144, v48
	v_fmac_f32 v161, v52, v136
	v_mul_f32_e32 v159, 0xbfb8aa3b, v160
	v_fmac_f32_dpp v161, v8, v140 row_shl:1 row_mask:0xf bank_mask:0xf
	v_exp_f32_e32 v159, v159
	v_fmac_f32_e32 v161, v140, v158
	v_mul_f32_e32 v158, 0xbfb8aa3b, v162
	v_exp_f32_e32 v158, v158
	v_add_f32_e32 v159, 1.0, v159
	v_rcp_f32_e32 v159, v159
	v_add_f32_e32 v158, 1.0, v158
	v_rcp_f32_e32 v158, v158
	v_mul_f32_e32 v159, v160, v159
	v_mul_f32_e32 v159, v174, v159
	v_mul_f32_e32 v160, 0xbfb8aa3b, v163
	v_mul_f32_e32 v158, v162, v158
	v_mul_f32_e32 v158, v175, v158
	v_cvt_pk_bf16_f32 v12, v158, v159
	v_mul_f32_e32 v159, 0xbfb8aa3b, v161
	v_exp_f32_e32 v159, v159
	v_exp_f32_e32 v160, v160
	v_add_f32_e32 v159, 1.0, v159
	v_rcp_f32_e32 v159, v159
	v_add_f32_e32 v160, 1.0, v160
	v_rcp_f32_e32 v160, v160
	v_mul_f32_e32 v159, v161, v159
	v_mul_f32_e32 v159, v173, v159
	v_mul_f32_e32 v160, v163, v160
	v_mul_f32_e32 v160, v172, v160
	v_cvt_pk_bf16_f32 v13, v159, v160
	s_nop 1
	v_permlane16_swap_b32 v10, v12
	v_permlane16_swap_b32 v11, v13
	s_or_b64 s[0:1], s[0:1], s[100:101]
	s_and_saveexec_b64 s[10:11], s[0:1]
	s_cbranch_execz .LBB0_1458
	v_cndmask_b32_e64 v162, v233, v234, s[98:99]
	v_add_u32_e32 v162, s74, v162
	v_mov_b64_e32 v[160:161], s[42:43]
	v_mad_i64_i32 v[160:161], s[0:1], v162, s90, v[160:161]
	v_lshl_add_u64 v[160:161], v[4:5], 1, v[160:161]
	v_cndmask_b32_e64 v158, 0, -8, s[98:99]
	v_ashrrev_i32_e32 v159, 31, v158
	v_lshl_add_u64 v[160:161], v[160:161], 0, v[158:159]
	global_store_dwordx4 v[160:161], v[10:13], off offset:128

.LBB0_1466:
	v_pk_mul_f32 v[160:161], v[214:215], v[160:161]
	s_waitcnt lgkmcnt(0)
	v_pk_mul_f32 v[166:167], v[208:209], v[166:167]
	v_fmac_f32_e32 v173, v152, v160
	v_fmac_f32_e32 v172, v153, v161
	v_pk_mul_f32 v[160:161], v[210:211], v[162:163]
	v_mul_f32_e32 v162, v142, v14
	v_fmac_f32_dpp v162, v18, v134 row_shr:1 row_mask:0xf bank_mask:0xf
	v_mul_f32_e32 v163, v143, v15
	v_pk_mul_f32 v[158:159], v[210:211], v[158:159]
	v_fmac_f32_e32 v162, v134, v166
	v_fmac_f32_dpp v163, v19, v135 row_shr:1 row_mask:0xf bank_mask:0xf
	v_fmac_f32_e32 v175, v150, v158
	v_fmac_f32_e32 v174, v151, v159
	v_pk_mul_f32 v[158:159], v[214:215], v[164:165]
	v_fmac_f32 v162, v26, v138
	v_fmac_f32_e32 v163, v135, v167
	v_mul_f32_e32 v164, 0xbfb8aa3b, v162
	v_fmac_f32 v163, v27, v139
	v_exp_f32_e32 v164, v164
	v_mul_f32_e32 v167, 0xbfb8aa3b, v163
	v_exp_f32_e32 v167, v167
	v_mul_f32_e32 v165, v144, v16
	v_add_f32_e32 v164, 1.0, v164
	v_rcp_f32_e32 v164, v164
	v_add_f32_e32 v167, 1.0, v167
	v_rcp_f32_e32 v167, v167
	v_pk_mul_f32 v[168:169], v[212:213], v[168:169]
	v_fmac_f32_dpp v165, v20, v136 row_shr:1 row_mask:0xf bank_mask:0xf
	v_mul_f32_e32 v166, v145, v17
	v_fmac_f32_e32 v165, v136, v168
	v_fmac_f32_dpp v166, v21, v137 row_shr:1 row_mask:0xf bank_mask:0xf
	v_fmac_f32 v165, v28, v140
	v_mul_f32_e32 v162, v162, v164
	v_fmac_f32_e32 v166, v137, v169
	v_mul_f32_e32 v164, 0xbfb8aa3b, v165
	v_fmac_f32 v166, v29, v141
	v_mul_f32_e32 v163, v163, v167
	v_exp_f32_e32 v164, v164
	v_mul_f32_e32 v167, 0xbfb8aa3b, v166
	v_exp_f32_e32 v167, v167
	v_mul_f32_e32 v162, v184, v162
	v_add_f32_e32 v164, 1.0, v164
	v_rcp_f32_e32 v168, v164
	v_add_f32_e32 v164, 1.0, v167
	v_rcp_f32_e32 v167, v164
	v_mul_f32_e32 v163, v185, v163
	v_cvt_pk_bf16_f32 v10, v162, v163
	v_mul_f32_e32 v162, v165, v168
	v_mul_f32_e32 v163, v166, v167
	v_mul_f32_e32 v162, v186, v162
	v_mul_f32_e32 v163, v187, v163
	v_cvt_pk_bf16_f32 v11, v162, v163
	v_add_u32_e32 v166, s74, v235
	v_mov_b64_e32 v[162:163], s[42:43]
	v_mad_i64_i32 v[166:167], s[0:1], v166, s90, v[162:163]
	v_lshl_add_u64 v[166:167], v[166:167], 0, v[170:171]
	v_mul_f32_e32 v164, v26, v142
	v_fmac_f32 v164, v14, v134
	v_mul_f32_e32 v165, v27, v143
	v_fmac_f32 v164, v22, v138
	v_fmac_f32 v165, v15, v135
	v_mul_f32_e32 v166, v28, v144
	v_mul_f32_e32 v168, 0xbfb8aa3b, v164
	v_exp_f32_e32 v168, v168
	v_fmac_f32 v165, v23, v139
	v_fmac_f32 v166, v16, v136
	v_mul_f32_e32 v167, v29, v145
	v_add_f32_e32 v168, 1.0, v168
	v_rcp_f32_e32 v168, v168
	v_fmac_f32 v166, v24, v140
	v_fmac_f32 v167, v17, v137
	s_nop 0
	v_mul_f32_e32 v164, v164, v168
	v_mul_f32_e32 v168, 0xbfb8aa3b, v165
	v_exp_f32_e32 v168, v168
	v_mul_f32_e32 v164, v183, v164
	v_fmac_f32 v167, v25, v141
	v_add_f32_e32 v168, 1.0, v168
	v_rcp_f32_e32 v168, v168
	s_nop 0
	v_mul_f32_e32 v165, v165, v168
	v_mul_f32_e32 v165, v182, v165
	v_cvt_pk_bf16_f32 v12, v164, v165
	v_mul_f32_e32 v165, 0xbfb8aa3b, v166
	v_exp_f32_e32 v165, v165
	s_nop 0
	v_add_f32_e32 v165, 1.0, v165
	v_rcp_f32_e32 v165, v165
	s_nop 0
	v_mul_f32_e32 v165, v166, v165
	v_mul_f32_e32 v166, 0xbfb8aa3b, v167
	v_exp_f32_e32 v166, v166
	v_mul_f32_e32 v165, v181, v165
	v_add_f32_e32 v166, 1.0, v166
	v_rcp_f32_e32 v166, v166
	s_nop 0
	v_mul_f32_e32 v166, v167, v166
	v_mul_f32_e32 v166, v180, v166
	v_cvt_pk_bf16_f32 v13, v165, v166
	s_nop 1
	v_permlane16_swap_b32 v10, v12
	v_permlane16_swap_b32 v11, v13
	v_cndmask_b32_e64 v166, v235, v236, s[98:99]
	v_add_u32_e32 v166, s74, v166
	v_mad_i64_i32 v[166:167], s[0:1], v166, s90, v[162:163]
	v_lshl_add_u64 v[166:167], v[166:167], 0, v[170:171]
	v_cndmask_b32_e64 v164, 0, -8, s[98:99]
	v_ashrrev_i32_e32 v165, 31, v164
	v_lshl_add_u64 v[166:167], v[166:167], 0, v[164:165]
	global_store_dwordx4 v[166:167], v[10:13], off offset:128
	v_mul_f32_e32 v164, v22, v142
	v_fmac_f32 v164, v26, v134
	v_mul_f32_e32 v165, v23, v143
	v_fmac_f32 v164, v18, v138
	v_fmac_f32 v165, v27, v135
	v_mul_f32_e32 v166, v24, v144
	v_mul_f32_e32 v168, 0xbfb8aa3b, v164
	v_exp_f32_e32 v168, v168
	v_fmac_f32 v165, v19, v139
	v_fmac_f32 v166, v28, v136
	v_mul_f32_e32 v167, v25, v145
	v_add_f32_e32 v168, 1.0, v168
	v_rcp_f32_e32 v168, v168
	v_fmac_f32 v166, v20, v140
	v_fmac_f32 v167, v29, v137
	s_nop 0
	v_mul_f32_e32 v164, v164, v168
	v_mul_f32_e32 v168, 0xbfb8aa3b, v165
	v_exp_f32_e32 v168, v168
	v_mul_f32_e32 v164, v179, v164
	v_fmac_f32 v167, v21, v141
	v_add_f32_e32 v168, 1.0, v168
	v_rcp_f32_e32 v168, v168
	s_nop 0
	v_mul_f32_e32 v165, v165, v168
	v_mul_f32_e32 v165, v178, v165
	v_cvt_pk_bf16_f32 v10, v164, v165
	v_mul_f32_e32 v165, 0xbfb8aa3b, v166
	v_exp_f32_e32 v165, v165
	s_nop 0
	v_add_f32_e32 v165, 1.0, v165
	v_rcp_f32_e32 v165, v165
	s_nop 0
	v_mul_f32_e32 v165, v166, v165
	v_mul_f32_e32 v166, 0xbfb8aa3b, v167
	v_exp_f32_e32 v166, v166
	v_mul_f32_e32 v165, v177, v165
	v_add_f32_e32 v166, 1.0, v166
	v_rcp_f32_e32 v166, v166
	s_nop 0
	v_mul_f32_e32 v166, v167, v166
	v_mul_f32_e32 v166, v176, v166
	v_cvt_pk_bf16_f32 v11, v165, v166
	v_add_u32_e32 v166, s74, v237
	v_mad_i64_i32 v[162:163], s[0:1], v166, s90, v[162:163]
	v_lshl_add_u64 v[162:163], v[162:163], 0, v[170:171]
	v_mul_f32_e32 v162, v142, v18
	v_fmac_f32 v162, v22, v134
	v_mul_f32_e32 v163, v145, v21
	v_fmac_f32_dpp v162, v14, v138 row_shl:1 row_mask:0xf bank_mask:0xf
	v_fmac_f32 v163, v25, v137
	s_or_b64 s[0:1], s[16:17], s[6:7]
	v_fmac_f32_e32 v162, v138, v160
	v_mul_f32_e32 v160, v143, v19
	v_fmac_f32 v160, v23, v135
	v_fmac_f32_dpp v163, v17, v141 row_shl:1 row_mask:0xf bank_mask:0xf
	s_nop 0
	v_fmac_f32_dpp v160, v15, v139 row_shl:1 row_mask:0xf bank_mask:0xf
	v_fmac_f32_e32 v163, v141, v159
	v_fmac_f32_e32 v160, v139, v161
	v_mul_f32_e32 v161, v144, v20
	v_fmac_f32 v161, v24, v136
	v_mul_f32_e32 v159, 0xbfb8aa3b, v160
	v_fmac_f32_dpp v161, v16, v140 row_shl:1 row_mask:0xf bank_mask:0xf
	v_exp_f32_e32 v159, v159
	v_fmac_f32_e32 v161, v140, v158
	v_mul_f32_e32 v158, 0xbfb8aa3b, v162
	v_exp_f32_e32 v158, v158
	v_add_f32_e32 v159, 1.0, v159
	v_rcp_f32_e32 v159, v159
	v_add_f32_e32 v158, 1.0, v158
	v_rcp_f32_e32 v158, v158
	v_mul_f32_e32 v159, v160, v159
	v_mul_f32_e32 v159, v174, v159
	v_mul_f32_e32 v160, 0xbfb8aa3b, v163
	v_mul_f32_e32 v158, v162, v158
	v_mul_f32_e32 v158, v175, v158
	v_cvt_pk_bf16_f32 v12, v158, v159
	v_mul_f32_e32 v159, 0xbfb8aa3b, v161
	v_exp_f32_e32 v159, v159
	v_exp_f32_e32 v160, v160
	v_add_f32_e32 v159, 1.0, v159
	v_rcp_f32_e32 v159, v159
	v_add_f32_e32 v160, 1.0, v160
	v_rcp_f32_e32 v160, v160
	v_mul_f32_e32 v159, v161, v159
	v_mul_f32_e32 v159, v173, v159
	v_mul_f32_e32 v160, v163, v160
	v_mul_f32_e32 v160, v172, v160
	v_cvt_pk_bf16_f32 v13, v159, v160
	s_nop 1
	v_permlane16_swap_b32 v10, v12
	v_permlane16_swap_b32 v11, v13
	s_or_b64 s[0:1], s[0:1], s[100:101]
	s_and_saveexec_b64 s[10:11], s[0:1]
	s_cbranch_execz .LBB0_1468
	v_cndmask_b32_e64 v162, v237, v238, s[98:99]
	v_add_u32_e32 v162, s74, v162
	v_mov_b64_e32 v[160:161], s[42:43]
	v_mad_i64_i32 v[160:161], s[0:1], v162, s90, v[160:161]
	v_lshl_add_u64 v[4:5], v[4:5], 1, v[160:161]
	v_cndmask_b32_e64 v158, 0, -8, s[98:99]
	v_ashrrev_i32_e32 v159, 31, v158
	v_lshl_add_u64 v[4:5], v[4:5], 0, v[158:159]
	global_store_dwordx4 v[4:5], v[10:13], off offset:128

.LBB0_1472:
	s_waitcnt lgkmcnt(0)
	s_barrier
	v_readfirstlane_b32 s98, v0
	s_lshr_b32 s98, s98, 6
	s_lshl_b32 s98, s98, 10
	s_add_i32 m0, s98, 0x8000
	v_lshl_add_u32 v4, v228, 2, s15
	s_waitcnt lgkmcnt(0)
	ds_read_b128 v[170:173], v4
	ds_read_b128 v[146:149], v4 offset:16
	ds_read_b128 v[158:161], v4 offset:512
	ds_read_b128 v[134:137], v4 offset:528
	ds_read_b128 v[178:181], v4 offset:1024
	ds_read_b128 v[154:157], v4 offset:1040
	ds_read_b128 v[166:169], v4 offset:1536
	ds_read_b128 v[142:145], v4 offset:1552
	ds_read_b128 v[174:177], v4 offset:2048
	ds_read_b128 v[150:153], v4 offset:2064
	ds_read_b128 v[162:165], v4 offset:2560
	ds_read_b128 v[138:141], v4 offset:2576
	s_and_b64 s[10:11], s[50:51], s[66:67]
	s_add_i32 s75, s72, 0x400
	v_mov_b32_e32 v182, 0
	s_and_b64 vcc, exec, s[10:11]
	v_mov_b32_e32 v186, 0
	v_mov_b32_e32 v187, 0
	v_mov_b32_e32 v188, 0
	v_mov_b32_e32 v189, 0
	s_cbranch_vccnz .LBB0_1474
	s_and_b64 s[0:1], s[50:51], exec
	s_cselect_b32 s0, s75, s88
	v_lshl_add_u32 v4, v228, 2, s0
	ds_read_b128 v[186:189], v4

.LBB0_1480:
	v_pk_mul_f32 v[130:131], v[210:211], v[182:183]
	s_waitcnt lgkmcnt(0)
	v_pk_mul_f32 v[126:127], v[208:209], v[126:127]
	v_fmac_f32_e32 v188, v174, v130
	v_fmac_f32_e32 v186, v175, v131
	v_pk_mul_f32 v[130:131], v[210:211], v[122:123]
	v_mul_f32_e32 v122, v166, v70
	v_fmac_f32_dpp v122, v110, v158 row_shr:1 row_mask:0xf bank_mask:0xf
	v_mul_f32_e32 v123, v167, v71
	v_fmac_f32_e32 v122, v158, v126
	v_fmac_f32_dpp v123, v111, v159 row_shr:1 row_mask:0xf bank_mask:0xf
	v_pk_mul_f32 v[132:133], v[212:213], v[128:129]
	v_pk_mul_f32 v[128:129], v[214:215], v[124:125]
	v_fmac_f32 v122, v118, v162
	v_fmac_f32_e32 v123, v159, v127
	v_mul_f32_e32 v124, 0xbfb8aa3b, v122
	v_fmac_f32 v123, v119, v163
	v_exp_f32_e32 v124, v124
	v_mul_f32_e32 v127, 0xbfb8aa3b, v123
	v_exp_f32_e32 v127, v127
	v_mul_f32_e32 v125, v168, v72
	v_add_f32_e32 v124, 1.0, v124
	v_rcp_f32_e32 v124, v124
	v_add_f32_e32 v127, 1.0, v127
	v_rcp_f32_e32 v127, v127
	v_fmac_f32_dpp v125, v112, v160 row_shr:1 row_mask:0xf bank_mask:0xf
	v_mul_f32_e32 v126, v169, v73
	v_fmac_f32_e32 v125, v160, v132
	v_fmac_f32_dpp v126, v113, v161 row_shr:1 row_mask:0xf bank_mask:0xf
	v_fmac_f32 v125, v120, v164
	v_mul_f32_e32 v122, v122, v124
	v_fmac_f32_e32 v126, v161, v133
	v_mul_f32_e32 v124, 0xbfb8aa3b, v125
	v_fmac_f32 v126, v121, v165
	v_mul_f32_e32 v123, v123, v127
	v_exp_f32_e32 v124, v124
	v_mul_f32_e32 v127, 0xbfb8aa3b, v126
	v_exp_f32_e32 v127, v127
	v_mul_f32_e32 v122, v221, v122
	v_add_f32_e32 v124, 1.0, v124
	v_rcp_f32_e32 v132, v124
	v_add_f32_e32 v124, 1.0, v127
	v_rcp_f32_e32 v127, v124
	v_pk_mul_f32 v[4:5], v[214:215], v[184:185]
	v_mul_f32_e32 v123, v220, v123
	v_cvt_pk_bf16_f32 v124, v122, v123
	v_mul_f32_e32 v122, v125, v132
	v_fmac_f32_e32 v187, v176, v4
	v_lshl_or_b32 v4, s14, 7, v228
	v_mul_f32_e32 v122, v222, v122
	v_mul_f32_e32 v123, v126, v127
	s_lshl_b32 s74, s94, 8
	v_fmac_f32_e32 v189, v177, v5
	v_ashrrev_i32_e32 v5, 31, v4
	v_mul_f32_e32 v123, v223, v123
	v_cvt_pk_bf16_f32 v125, v122, v123
	v_add_u32_e32 v122, s74, v230
	v_mov_b64_e32 v[132:133], s[42:43]
	v_mad_i64_i32 v[122:123], s[0:1], v122, s90, v[132:133]
	v_lshlrev_b64 v[126:127], 1, v[4:5]
	v_lshl_add_u64 v[122:123], v[122:123], 0, v[126:127]
	ds_write_addtid_b32 v124 offset:0
	ds_write_addtid_b32 v125 offset:256
	v_mul_f32_e32 v124, v118, v166
	v_fmac_f32 v124, v70, v158
	v_mul_f32_e32 v125, v119, v167
	v_fmac_f32 v124, v114, v162
	v_fmac_f32 v125, v71, v159
	v_mul_f32_e32 v183, v120, v168
	v_mul_f32_e32 v182, 0xbfb8aa3b, v124
	v_exp_f32_e32 v182, v182
	v_fmac_f32 v125, v115, v163
	v_fmac_f32 v183, v72, v160
	v_mul_f32_e32 v184, v121, v169
	v_add_f32_e32 v182, 1.0, v182
	v_rcp_f32_e32 v182, v182
	v_fmac_f32 v183, v116, v164
	v_fmac_f32 v184, v73, v161
	s_nop 0
	v_mul_f32_e32 v124, v124, v182
	v_mul_f32_e32 v182, 0xbfb8aa3b, v125
	v_exp_f32_e32 v182, v182
	v_mul_f32_e32 v124, v197, v124
	v_fmac_f32 v184, v117, v165
	v_add_f32_e32 v182, 1.0, v182
	v_rcp_f32_e32 v182, v182
	s_nop 0
	v_mul_f32_e32 v125, v125, v182
	v_mul_f32_e32 v125, v196, v125
	v_cvt_pk_bf16_f32 v182, v124, v125
	v_mul_f32_e32 v124, 0xbfb8aa3b, v183
	v_exp_f32_e32 v124, v124
	v_mul_f32_e32 v125, 0xbfb8aa3b, v184
	v_exp_f32_e32 v125, v125
	v_add_f32_e32 v124, 1.0, v124
	v_rcp_f32_e32 v124, v124
	v_add_f32_e32 v125, 1.0, v125
	v_rcp_f32_e32 v125, v125
	v_mul_f32_e32 v124, v183, v124
	v_mul_f32_e32 v124, v195, v124
	v_mul_f32_e32 v125, v184, v125
	v_mul_f32_e32 v125, v194, v125
	v_cvt_pk_bf16_f32 v183, v124, v125
	v_add_u32_e32 v124, s74, v232
	v_mad_i64_i32 v[124:125], s[0:1], v124, s90, v[132:133]
	v_lshl_add_u64 v[124:125], v[124:125], 0, v[126:127]
	ds_write_addtid_b32 v182 offset:512
	ds_write_addtid_b32 v183 offset:768
	v_mul_f32_e32 v182, v114, v166
	v_fmac_f32 v182, v118, v158
	v_mul_f32_e32 v118, v115, v167
	v_fmac_f32 v118, v119, v159
	v_mul_f32_e32 v119, v116, v168
	v_mul_f32_e32 v183, v117, v169
	v_fmac_f32 v182, v110, v162
	v_fmac_f32 v118, v111, v163
	v_fmac_f32 v119, v120, v160
	v_fmac_f32 v183, v121, v161
	s_nop 0
	v_mul_f32_e32 v120, 0xbfb8aa3b, v182
	v_mul_f32_e32 v121, 0xbfb8aa3b, v118
	v_exp_f32_e32 v120, v120
	v_exp_f32_e32 v121, v121
	v_fmac_f32 v119, v112, v164
	v_fmac_f32 v183, v113, v165
	v_add_f32_e32 v120, 1.0, v120
	v_add_f32_e32 v121, 1.0, v121
	v_rcp_f32_e32 v120, v120
	v_rcp_f32_e32 v121, v121
	v_mul_f32_e32 v120, v182, v120
	v_mul_f32_e32 v118, v118, v121
	v_mul_f32_e32 v120, v193, v120
	v_mul_f32_e32 v118, v192, v118
	v_cvt_pk_bf16_f32 v120, v120, v118
	v_mul_f32_e32 v118, 0xbfb8aa3b, v119
	v_exp_f32_e32 v118, v118
	s_nop 0
	v_add_f32_e32 v118, 1.0, v118
	v_rcp_f32_e32 v118, v118
	s_nop 0
	v_mul_f32_e32 v118, v119, v118
	v_mul_f32_e32 v119, 0xbfb8aa3b, v183
	v_exp_f32_e32 v119, v119
	v_mul_f32_e32 v118, v191, v118
	v_add_f32_e32 v119, 1.0, v119
	v_rcp_f32_e32 v119, v119
	s_nop 0
	v_mul_f32_e32 v119, v183, v119
	v_mul_f32_e32 v119, v190, v119
	v_cvt_pk_bf16_f32 v121, v118, v119
	v_add_u32_e32 v118, s74, v233
	v_mad_i64_i32 v[118:119], s[0:1], v118, s90, v[132:133]
	v_lshl_add_u64 v[118:119], v[118:119], 0, v[126:127]
	ds_write_addtid_b32 v120 offset:8192
	ds_write_addtid_b32 v121 offset:8448
	v_mul_f32_e32 v110, v166, v110
	v_fmac_f32 v110, v114, v158
	v_mul_f32_e32 v111, v167, v111
	v_fmac_f32_dpp v110, v70, v162 row_shl:1 row_mask:0xf bank_mask:0xf
	v_fmac_f32 v111, v115, v159
	v_mul_f32_e32 v112, v168, v112
	v_fmac_f32_e32 v110, v162, v130
	v_fmac_f32_dpp v111, v71, v163 row_shl:1 row_mask:0xf bank_mask:0xf
	v_mul_f32_e32 v114, 0xbfb8aa3b, v110
	v_fmac_f32_e32 v111, v163, v131
	v_exp_f32_e32 v114, v114
	v_mul_f32_e32 v115, 0xbfb8aa3b, v111
	v_exp_f32_e32 v115, v115
	v_fmac_f32 v112, v116, v160
	v_add_f32_e32 v114, 1.0, v114
	v_rcp_f32_e32 v114, v114
	v_add_f32_e32 v115, 1.0, v115
	v_mul_f32_e32 v113, v169, v113
	v_rcp_f32_e32 v115, v115
	v_fmac_f32_dpp v112, v72, v164 row_shl:1 row_mask:0xf bank_mask:0xf
	v_fmac_f32 v113, v117, v161
	v_mul_f32_e32 v110, v110, v114
	v_fmac_f32_e32 v112, v164, v128
	v_fmac_f32_dpp v113, v73, v165 row_shl:1 row_mask:0xf bank_mask:0xf
	v_mul_f32_e32 v114, 0xbfb8aa3b, v112
	v_fmac_f32_e32 v113, v165, v129
	v_mul_f32_e32 v111, v111, v115
	v_exp_f32_e32 v114, v114
	v_mul_f32_e32 v115, 0xbfb8aa3b, v113
	v_exp_f32_e32 v115, v115
	v_mul_f32_e32 v110, v188, v110
	v_add_f32_e32 v114, 1.0, v114
	v_rcp_f32_e32 v114, v114
	v_add_f32_e32 v115, 1.0, v115
	v_rcp_f32_e32 v115, v115
	v_mul_f32_e32 v111, v186, v111
	v_cvt_pk_bf16_f32 v110, v110, v111
	v_mul_f32_e32 v111, v112, v114
	v_mul_f32_e32 v111, v187, v111
	v_mul_f32_e32 v112, v113, v115
	s_or_b64 s[70:71], s[16:17], s[4:5]
	v_add_u32_e32 v120, s74, v234
	v_mul_f32_e32 v112, v189, v112
	v_cvt_pk_bf16_f32 v111, v111, v112
	s_and_saveexec_b64 s[10:11], s[70:71]
	s_cbranch_execz .LBB0_1482
	v_mov_b64_e32 v[112:113], s[42:43]
	v_mad_i64_i32 v[112:113], s[0:1], v120, s90, v[112:113]
	v_lshl_add_u64 v[112:113], v[4:5], 1, v[112:113]
	ds_write_addtid_b32 v110 offset:8704
	ds_write_addtid_b32 v111 offset:8960

.LBB0_1490:
	v_pk_mul_f32 v[102:103], v[214:215], v[112:113]
	v_pk_mul_f32 v[110:111], v[210:211], v[110:111]
	v_fmac_f32_e32 v107, v176, v102
	v_fmac_f32_e32 v104, v177, v103
	s_waitcnt lgkmcnt(0)
	v_pk_mul_f32 v[102:103], v[212:213], v[100:101]
	v_pk_mul_f32 v[100:101], v[210:211], v[94:95]
	v_mul_f32_e32 v94, v166, v74
	v_fmac_f32_e32 v108, v174, v110
	v_fmac_f32_e32 v106, v175, v111
	v_pk_mul_f32 v[110:111], v[208:209], v[98:99]
	v_fmac_f32_dpp v94, v78, v158 row_shr:1 row_mask:0xf bank_mask:0xf
	v_mul_f32_e32 v95, v167, v75
	v_fmac_f32_e32 v94, v158, v110
	v_fmac_f32_dpp v95, v79, v159 row_shr:1 row_mask:0xf bank_mask:0xf
	v_pk_mul_f32 v[98:99], v[214:215], v[96:97]
	v_fmac_f32 v94, v90, v162
	v_fmac_f32_e32 v95, v159, v111
	v_mul_f32_e32 v96, 0xbfb8aa3b, v94
	v_fmac_f32 v95, v91, v163
	v_exp_f32_e32 v96, v96
	v_mul_f32_e32 v105, 0xbfb8aa3b, v95
	v_mul_f32_e32 v97, v168, v76
	v_exp_f32_e32 v105, v105
	v_fmac_f32_dpp v97, v80, v160 row_shr:1 row_mask:0xf bank_mask:0xf
	v_add_f32_e32 v96, 1.0, v96
	v_fmac_f32_e32 v97, v160, v102
	v_mul_f32_e32 v102, v169, v77
	v_fmac_f32_dpp v102, v81, v161 row_shr:1 row_mask:0xf bank_mask:0xf
	v_rcp_f32_e32 v96, v96
	v_fmac_f32_e32 v102, v161, v103
	v_add_f32_e32 v103, 1.0, v105
	v_rcp_f32_e32 v103, v103
	v_fmac_f32 v97, v92, v164
	v_mul_f32_e32 v94, v94, v96
	v_mul_f32_e32 v96, 0xbfb8aa3b, v97
	v_fmac_f32 v102, v93, v165
	v_mul_f32_e32 v95, v95, v103
	v_exp_f32_e32 v96, v96
	v_mul_f32_e32 v103, 0xbfb8aa3b, v102
	v_exp_f32_e32 v103, v103
	v_mul_f32_e32 v94, v131, v94
	v_add_f32_e32 v96, 1.0, v96
	v_rcp_f32_e32 v105, v96
	v_add_f32_e32 v96, 1.0, v103
	v_rcp_f32_e32 v103, v96
	v_mul_f32_e32 v95, v132, v95
	v_cvt_pk_bf16_f32 v96, v94, v95
	v_mul_f32_e32 v94, v97, v105
	v_mul_f32_e32 v94, v133, v94
	v_mul_f32_e32 v95, v102, v103
	v_mul_f32_e32 v95, v182, v95
	v_cvt_pk_bf16_f32 v97, v94, v95
	v_add_u32_e32 v94, s74, v235
	v_mov_b64_e32 v[102:103], s[42:43]
	v_mad_i64_i32 v[94:95], s[0:1], v94, s90, v[102:103]
	v_lshl_add_u64 v[94:95], v[94:95], 0, v[126:127]
	ds_write_addtid_b32 v96 offset:16384
	ds_write_addtid_b32 v97 offset:16640
	v_mul_f32_e32 v96, v90, v166
	v_fmac_f32 v96, v74, v158
	v_mul_f32_e32 v97, v91, v167
	v_fmac_f32 v96, v86, v162
	v_fmac_f32 v97, v75, v159
	v_mul_f32_e32 v105, v92, v168
	v_mul_f32_e32 v110, 0xbfb8aa3b, v96
	v_exp_f32_e32 v110, v110
	v_fmac_f32 v97, v87, v163
	v_fmac_f32 v105, v76, v160
	v_mul_f32_e32 v109, v93, v169
	v_add_f32_e32 v110, 1.0, v110
	v_rcp_f32_e32 v110, v110
	v_fmac_f32 v105, v88, v164
	v_fmac_f32 v109, v77, v161
	s_nop 0
	v_mul_f32_e32 v96, v96, v110
	v_mul_f32_e32 v110, 0xbfb8aa3b, v97
	v_exp_f32_e32 v110, v110
	v_mul_f32_e32 v96, v130, v96
	v_fmac_f32 v109, v89, v165
	v_add_f32_e32 v110, 1.0, v110
	v_rcp_f32_e32 v110, v110
	s_nop 0
	v_mul_f32_e32 v97, v97, v110
	v_mul_f32_e32 v97, v129, v97
	v_cvt_pk_bf16_f32 v110, v96, v97
	v_mul_f32_e32 v96, 0xbfb8aa3b, v105
	v_exp_f32_e32 v96, v96
	v_mul_f32_e32 v97, 0xbfb8aa3b, v109
	v_exp_f32_e32 v97, v97
	v_add_f32_e32 v96, 1.0, v96
	v_rcp_f32_e32 v96, v96
	v_add_f32_e32 v97, 1.0, v97
	v_rcp_f32_e32 v97, v97
	v_mul_f32_e32 v96, v105, v96
	v_mul_f32_e32 v96, v128, v96
	v_mul_f32_e32 v97, v109, v97
	v_mul_f32_e32 v97, v121, v97
	v_cvt_pk_bf16_f32 v111, v96, v97
	v_add_u32_e32 v96, s74, v236
	v_mad_i64_i32 v[96:97], s[0:1], v96, s90, v[102:103]
	v_lshl_add_u64 v[96:97], v[96:97], 0, v[126:127]
	ds_write_addtid_b32 v110 offset:16896
	ds_write_addtid_b32 v111 offset:17152
	v_mul_f32_e32 v105, v86, v166
	v_fmac_f32 v105, v90, v158
	v_mul_f32_e32 v90, v87, v167
	v_fmac_f32 v90, v91, v159
	v_mul_f32_e32 v91, v88, v168
	v_mul_f32_e32 v109, v89, v169
	v_fmac_f32 v105, v78, v162
	v_fmac_f32 v90, v79, v163
	v_fmac_f32 v91, v92, v160
	v_fmac_f32 v109, v93, v161
	s_nop 0
	v_mul_f32_e32 v92, 0xbfb8aa3b, v105
	v_mul_f32_e32 v93, 0xbfb8aa3b, v90
	v_exp_f32_e32 v92, v92
	v_exp_f32_e32 v93, v93
	v_fmac_f32 v91, v80, v164
	v_fmac_f32 v109, v81, v165
	v_add_f32_e32 v92, 1.0, v92
	v_add_f32_e32 v93, 1.0, v93
	v_rcp_f32_e32 v92, v92
	v_rcp_f32_e32 v93, v93
	v_mul_f32_e32 v92, v105, v92
	v_mul_f32_e32 v90, v90, v93
	v_mul_f32_e32 v92, v117, v92
	v_mul_f32_e32 v90, v116, v90
	v_cvt_pk_bf16_f32 v92, v92, v90
	v_mul_f32_e32 v90, 0xbfb8aa3b, v91
	v_exp_f32_e32 v90, v90
	s_nop 0
	v_add_f32_e32 v90, 1.0, v90
	v_rcp_f32_e32 v90, v90
	s_nop 0
	v_mul_f32_e32 v90, v91, v90
	v_mul_f32_e32 v91, 0xbfb8aa3b, v109
	v_exp_f32_e32 v91, v91
	v_mul_f32_e32 v90, v115, v90
	v_add_f32_e32 v91, 1.0, v91
	v_rcp_f32_e32 v91, v91
	s_nop 0
	v_mul_f32_e32 v91, v109, v91
	v_mul_f32_e32 v91, v114, v91
	v_cvt_pk_bf16_f32 v93, v90, v91
	v_add_u32_e32 v90, s74, v237
	v_mad_i64_i32 v[90:91], s[0:1], v90, s90, v[102:103]
	v_lshl_add_u64 v[90:91], v[90:91], 0, v[126:127]
	ds_write_addtid_b32 v92 offset:24576
	ds_write_addtid_b32 v93 offset:24832
	v_mul_f32_e32 v78, v166, v78
	v_fmac_f32 v78, v86, v158
	s_or_b64 s[66:67], s[16:17], s[6:7]
	v_fmac_f32_dpp v78, v74, v162 row_shl:1 row_mask:0xf bank_mask:0xf
	v_mul_f32_e32 v74, v167, v79
	v_fmac_f32 v74, v87, v159
	v_fmac_f32_e32 v78, v162, v100
	v_fmac_f32_dpp v74, v75, v163 row_shl:1 row_mask:0xf bank_mask:0xf
	v_mul_f32_e32 v79, 0xbfb8aa3b, v78
	v_fmac_f32_e32 v74, v163, v101
	v_mul_f32_e32 v75, v168, v80
	v_exp_f32_e32 v79, v79
	v_mul_f32_e32 v80, 0xbfb8aa3b, v74
	v_fmac_f32 v75, v88, v160
	v_exp_f32_e32 v80, v80
	v_fmac_f32_dpp v75, v76, v164 row_shl:1 row_mask:0xf bank_mask:0xf
	v_mul_f32_e32 v76, v169, v81
	v_fmac_f32 v76, v89, v161
	v_fmac_f32_e32 v75, v164, v98
	v_fmac_f32_dpp v76, v77, v165 row_shl:1 row_mask:0xf bank_mask:0xf
	v_add_f32_e32 v77, 1.0, v79
	v_rcp_f32_e32 v77, v77
	v_add_f32_e32 v79, 1.0, v80
	v_rcp_f32_e32 v79, v79
	v_fmac_f32_e32 v76, v165, v99
	v_mul_f32_e32 v77, v78, v77
	v_mul_f32_e32 v78, 0xbfb8aa3b, v75
	v_mul_f32_e32 v74, v74, v79
	v_exp_f32_e32 v78, v78
	v_mul_f32_e32 v79, 0xbfb8aa3b, v76
	v_exp_f32_e32 v79, v79
	v_mul_f32_e32 v74, v106, v74
	v_add_f32_e32 v78, 1.0, v78
	v_rcp_f32_e32 v78, v78
	v_add_f32_e32 v79, 1.0, v79
	v_rcp_f32_e32 v79, v79
	v_mul_f32_e32 v77, v108, v77
	v_mul_f32_e32 v75, v75, v78
	v_mul_f32_e32 v75, v107, v75
	v_mul_f32_e32 v76, v76, v79
	v_add_u32_e32 v78, s74, v238
	v_cvt_pk_bf16_f32 v74, v77, v74
	v_mul_f32_e32 v76, v104, v76
	v_cvt_pk_bf16_f32 v75, v75, v76
	s_and_saveexec_b64 s[16:17], s[66:67]
	s_cbranch_execz .LBB0_1492
	v_mov_b64_e32 v[76:77], s[42:43]
	v_mad_i64_i32 v[76:77], s[0:1], v78, s90, v[76:77]
	v_lshl_add_u64 v[76:77], v[4:5], 1, v[76:77]
	ds_write_addtid_b32 v74 offset:25088
	ds_write_addtid_b32 v75 offset:25344

.LBB0_1502:
	v_pk_mul_f32 v[70:71], v[210:211], v[70:71]
	s_waitcnt lgkmcnt(0)
	ds_read_addtid_b32 v98 offset:0
	ds_read_addtid_b32 v99 offset:256
	v_pk_mul_f32 v[62:63], v[208:209], v[62:63]
	v_fmac_f32_e32 v68, v150, v70
	v_mul_f32_e32 v70, v142, v6
	v_fmac_f32_dpp v70, v46, v134 row_shr:1 row_mask:0xf bank_mask:0xf
	v_pk_mul_f32 v[72:73], v[214:215], v[72:73]
	v_fmac_f32_e32 v70, v134, v62
	v_mul_f32_e32 v62, v143, v7
	v_fmac_f32_dpp v62, v47, v135 row_shr:1 row_mask:0xf bank_mask:0xf
	v_fmac_f32_e32 v66, v151, v71
	v_fmac_f32 v70, v54, v138
	v_fmac_f32_e32 v62, v135, v63
	v_mul_f32_e32 v71, 0xbfb8aa3b, v70
	v_fmac_f32_e32 v67, v152, v72
	v_fmac_f32 v62, v55, v139
	v_mul_f32_e32 v63, v144, v8
	v_exp_f32_e32 v71, v71
	v_mul_f32_e32 v72, 0xbfb8aa3b, v62
	v_pk_mul_f32 v[64:65], v[212:213], v[64:65]
	v_fmac_f32_dpp v63, v48, v136 row_shr:1 row_mask:0xf bank_mask:0xf
	v_exp_f32_e32 v72, v72
	v_fmac_f32_e32 v63, v136, v64
	v_mul_f32_e32 v64, v145, v9
	v_fmac_f32_dpp v64, v49, v137 row_shr:1 row_mask:0xf bank_mask:0xf
	v_fmac_f32 v63, v56, v140
	v_fmac_f32_e32 v69, v153, v73
	v_fmac_f32_e32 v64, v137, v65
	v_add_f32_e32 v65, 1.0, v71
	v_rcp_f32_e32 v65, v65
	v_add_f32_e32 v71, 1.0, v72
	v_rcp_f32_e32 v71, v71
	v_fmac_f32 v64, v57, v141
	v_mul_f32_e32 v65, v70, v65
	v_mul_f32_e32 v70, 0xbfb8aa3b, v63
	v_mul_f32_e32 v62, v62, v71
	v_exp_f32_e32 v70, v70
	v_mul_f32_e32 v71, 0xbfb8aa3b, v64
	v_exp_f32_e32 v71, v71
	v_mul_f32_e32 v62, v83, v62
	v_add_f32_e32 v70, 1.0, v70
	v_rcp_f32_e32 v70, v70
	v_add_f32_e32 v71, 1.0, v71
	v_rcp_f32_e32 v71, v71
	v_pk_mul_f32 v[60:61], v[214:215], v[60:61]
	v_mul_f32_e32 v63, v63, v70
	v_mul_f32_e32 v63, v85, v63
	v_mul_f32_e32 v64, v64, v71
	v_pk_mul_f32 v[58:59], v[210:211], v[58:59]
	v_mul_f32_e32 v65, v84, v65
	v_cvt_pk_bf16_f32 v100, v65, v62
	v_mul_f32_e32 v64, v86, v64
	v_cvt_pk_bf16_f32 v101, v63, v64
	s_waitcnt lgkmcnt(0)
	global_store_dwordx4 v[122:123], v[98:101], off
	ds_read_addtid_b32 v84 offset:512
	ds_read_addtid_b32 v85 offset:768
	v_mul_f32_e32 v62, v54, v142
	v_fmac_f32 v62, v6, v134
	v_mul_f32_e32 v63, v55, v143
	v_fmac_f32 v62, v50, v138
	v_fmac_f32 v63, v7, v135
	v_mul_f32_e32 v64, v56, v144
	v_mul_f32_e32 v70, 0xbfb8aa3b, v62
	v_exp_f32_e32 v70, v70
	v_fmac_f32 v63, v51, v139
	v_fmac_f32 v64, v8, v136
	v_mul_f32_e32 v65, v57, v145
	v_add_f32_e32 v70, 1.0, v70
	v_rcp_f32_e32 v70, v70
	v_fmac_f32 v64, v52, v140
	v_fmac_f32 v65, v9, v137
	s_nop 0
	v_mul_f32_e32 v62, v62, v70
	v_mul_f32_e32 v70, 0xbfb8aa3b, v63
	v_exp_f32_e32 v70, v70
	v_mul_f32_e32 v62, v82, v62
	v_fmac_f32 v65, v53, v141
	v_add_f32_e32 v70, 1.0, v70
	v_rcp_f32_e32 v70, v70
	s_nop 0
	v_mul_f32_e32 v63, v63, v70
	v_mul_f32_e32 v63, v81, v63
	v_cvt_pk_bf16_f32 v86, v62, v63
	v_mul_f32_e32 v63, 0xbfb8aa3b, v64
	v_exp_f32_e32 v63, v63
	s_nop 0
	v_add_f32_e32 v63, 1.0, v63
	v_rcp_f32_e32 v63, v63
	s_nop 0
	v_mul_f32_e32 v63, v64, v63
	v_mul_f32_e32 v64, 0xbfb8aa3b, v65
	v_exp_f32_e32 v64, v64
	v_mul_f32_e32 v63, v80, v63
	v_add_f32_e32 v64, 1.0, v64
	v_rcp_f32_e32 v64, v64
	s_nop 0
	v_mul_f32_e32 v64, v65, v64
	v_mul_f32_e32 v64, v79, v64
	v_cvt_pk_bf16_f32 v87, v63, v64
	s_waitcnt lgkmcnt(0)
	global_store_dwordx4 v[124:125], v[84:87], off
	ds_read_addtid_b32 v70 offset:8192
	ds_read_addtid_b32 v71 offset:8448
	v_mul_f32_e32 v62, v50, v142
	v_fmac_f32 v62, v54, v134
	v_mul_f32_e32 v54, v51, v143
	v_fmac_f32 v54, v55, v135
	v_mul_f32_e32 v55, v52, v144
	v_fmac_f32 v55, v56, v136
	v_mul_f32_e32 v56, v53, v145
	v_fmac_f32 v62, v46, v138
	v_fmac_f32 v56, v57, v137
	v_fmac_f32 v54, v47, v139
	v_fmac_f32 v55, v48, v140
	s_nop 0
	v_mul_f32_e32 v57, 0xbfb8aa3b, v62
	v_exp_f32_e32 v57, v57
	v_fmac_f32 v56, v49, v141
	s_nop 0
	v_add_f32_e32 v57, 1.0, v57
	v_rcp_f32_e32 v57, v57
	s_nop 0
	v_mul_f32_e32 v57, v62, v57
	v_mul_f32_e32 v62, 0xbfb8aa3b, v54
	v_exp_f32_e32 v62, v62
	v_mul_f32_e32 v57, v77, v57
	v_add_f32_e32 v62, 1.0, v62
	v_rcp_f32_e32 v62, v62
	s_nop 0
	v_mul_f32_e32 v54, v54, v62
	v_mul_f32_e32 v54, v76, v54
	v_cvt_pk_bf16_f32 v72, v57, v54
	v_mul_f32_e32 v57, 0xbfb8aa3b, v55
	v_exp_f32_e32 v57, v57
	s_nop 0
	v_add_f32_e32 v57, 1.0, v57
	v_rcp_f32_e32 v57, v57
	s_nop 0
	v_mul_f32_e32 v55, v55, v57
	v_mul_f32_e32 v57, 0xbfb8aa3b, v56
	v_exp_f32_e32 v57, v57
	v_mul_f32_e32 v55, v75, v55
	v_add_f32_e32 v57, 1.0, v57
	v_rcp_f32_e32 v57, v57
	s_nop 0
	v_mul_f32_e32 v56, v56, v57
	v_mul_f32_e32 v56, v74, v56
	v_cvt_pk_bf16_f32 v73, v55, v56
	s_waitcnt lgkmcnt(0)
	global_store_dwordx4 v[118:119], v[70:73], off
	ds_read_addtid_b32 v54 offset:8704
	ds_read_addtid_b32 v55 offset:8960
	v_mul_f32_e32 v46, v142, v46
	v_fmac_f32 v46, v50, v134
	v_mul_f32_e32 v47, v143, v47
	v_fmac_f32_dpp v46, v6, v138 row_shl:1 row_mask:0xf bank_mask:0xf
	v_fmac_f32 v47, v51, v135
	v_mul_f32_e32 v48, v144, v48
	v_fmac_f32_e32 v46, v138, v58
	v_fmac_f32_dpp v47, v7, v139 row_shl:1 row_mask:0xf bank_mask:0xf
	v_mul_f32_e32 v50, 0xbfb8aa3b, v46
	v_fmac_f32_e32 v47, v139, v59
	v_exp_f32_e32 v50, v50
	v_mul_f32_e32 v51, 0xbfb8aa3b, v47
	v_exp_f32_e32 v51, v51
	v_fmac_f32 v48, v52, v136
	v_add_f32_e32 v50, 1.0, v50
	v_rcp_f32_e32 v50, v50
	v_add_f32_e32 v51, 1.0, v51
	v_mul_f32_e32 v49, v145, v49
	v_rcp_f32_e32 v51, v51
	v_fmac_f32_dpp v48, v8, v140 row_shl:1 row_mask:0xf bank_mask:0xf
	v_fmac_f32 v49, v53, v137
	v_mul_f32_e32 v46, v46, v50
	v_fmac_f32_e32 v48, v140, v60
	v_fmac_f32_dpp v49, v9, v141 row_shl:1 row_mask:0xf bank_mask:0xf
	v_mul_f32_e32 v50, 0xbfb8aa3b, v48
	v_fmac_f32_e32 v49, v141, v61
	v_mul_f32_e32 v47, v47, v51
	v_exp_f32_e32 v50, v50
	v_mul_f32_e32 v51, 0xbfb8aa3b, v49
	v_exp_f32_e32 v51, v51
	v_mul_f32_e32 v46, v68, v46
	v_add_f32_e32 v50, 1.0, v50
	v_rcp_f32_e32 v50, v50
	v_add_f32_e32 v51, 1.0, v51
	v_rcp_f32_e32 v51, v51
	v_mul_f32_e32 v47, v66, v47
	v_cvt_pk_bf16_f32 v56, v46, v47
	v_mul_f32_e32 v47, v48, v50
	v_mul_f32_e32 v47, v67, v47
	v_mul_f32_e32 v48, v49, v51
	v_mul_f32_e32 v48, v69, v48
	v_cvt_pk_bf16_f32 v57, v47, v48
	s_and_saveexec_b64 s[8:9], s[70:71]
	s_cbranch_execz .LBB0_1504
	v_mov_b64_e32 v[48:49], s[42:43]
	v_mad_i64_i32 v[48:49], s[0:1], v120, s90, v[48:49]
	v_lshl_add_u64 v[48:49], v[4:5], 1, v[48:49]
	s_waitcnt lgkmcnt(0)
	global_store_dwordx4 v[48:49], v[54:57], off

.LBB0_1512:
	v_mul_f32_e32 v41, v142, v14
	s_waitcnt lgkmcnt(0)
	ds_read_addtid_b32 v60 offset:16384
	ds_read_addtid_b32 v61 offset:16640
	v_pk_mul_f32 v[34:35], v[208:209], v[34:35]
	v_fmac_f32_dpp v41, v18, v134 row_shr:1 row_mask:0xf bank_mask:0xf
	v_pk_mul_f32 v[46:47], v[210:211], v[46:47]
	v_fmac_f32_e32 v41, v134, v34
	v_mul_f32_e32 v34, v143, v15
	v_fmac_f32_dpp v34, v19, v135 row_shr:1 row_mask:0xf bank_mask:0xf
	v_fmac_f32 v41, v26, v138
	v_fmac_f32_e32 v42, v150, v46
	v_fmac_f32_e32 v34, v135, v35
	v_mul_f32_e32 v45, 0xbfb8aa3b, v41
	v_fmac_f32 v34, v27, v139
	v_mul_f32_e32 v35, v144, v16
	v_exp_f32_e32 v45, v45
	v_mul_f32_e32 v46, 0xbfb8aa3b, v34
	v_pk_mul_f32 v[36:37], v[212:213], v[36:37]
	v_fmac_f32_dpp v35, v20, v136 row_shr:1 row_mask:0xf bank_mask:0xf
	v_exp_f32_e32 v46, v46
	v_fmac_f32_e32 v35, v136, v36
	v_mul_f32_e32 v36, v145, v17
	v_fmac_f32_dpp v36, v21, v137 row_shr:1 row_mask:0xf bank_mask:0xf
	v_fmac_f32 v35, v28, v140
	v_pk_mul_f32 v[48:49], v[214:215], v[48:49]
	v_fmac_f32_e32 v36, v137, v37
	v_add_f32_e32 v37, 1.0, v45
	v_rcp_f32_e32 v37, v37
	v_add_f32_e32 v45, 1.0, v46
	v_rcp_f32_e32 v45, v45
	v_fmac_f32 v36, v29, v141
	v_mul_f32_e32 v37, v41, v37
	v_mul_f32_e32 v41, 0xbfb8aa3b, v35
	v_mul_f32_e32 v34, v34, v45
	v_exp_f32_e32 v41, v41
	v_mul_f32_e32 v45, 0xbfb8aa3b, v36
	v_exp_f32_e32 v45, v45
	v_mul_f32_e32 v34, v57, v34
	v_add_f32_e32 v41, 1.0, v41
	v_rcp_f32_e32 v41, v41
	v_add_f32_e32 v45, 1.0, v45
	v_rcp_f32_e32 v45, v45
	v_fmac_f32_e32 v38, v151, v47
	v_mul_f32_e32 v35, v35, v41
	v_mul_f32_e32 v35, v58, v35
	v_mul_f32_e32 v36, v36, v45
	v_fmac_f32_e32 v39, v152, v48
	v_fmac_f32_e32 v40, v153, v49
	v_pk_mul_f32 v[32:33], v[214:215], v[32:33]
	v_pk_mul_f32 v[30:31], v[210:211], v[30:31]
	v_mul_f32_e32 v37, v56, v37
	v_cvt_pk_bf16_f32 v62, v37, v34
	v_mul_f32_e32 v36, v59, v36
	v_cvt_pk_bf16_f32 v63, v35, v36
	s_waitcnt lgkmcnt(0)
	global_store_dwordx4 v[94:95], v[60:63], off
	ds_read_addtid_b32 v46 offset:16896
	ds_read_addtid_b32 v47 offset:17152
	v_mul_f32_e32 v34, v26, v142
	v_fmac_f32 v34, v14, v134
	v_mul_f32_e32 v35, v27, v143
	v_fmac_f32 v34, v22, v138
	v_fmac_f32 v35, v15, v135
	v_mul_f32_e32 v36, v28, v144
	v_mul_f32_e32 v41, 0xbfb8aa3b, v34
	v_fmac_f32 v35, v23, v139
	v_exp_f32_e32 v41, v41
	v_mul_f32_e32 v45, 0xbfb8aa3b, v35
	v_exp_f32_e32 v45, v45
	v_fmac_f32 v36, v16, v136
	v_add_f32_e32 v41, 1.0, v41
	v_rcp_f32_e32 v41, v41
	v_add_f32_e32 v45, 1.0, v45
	v_rcp_f32_e32 v45, v45
	v_mul_f32_e32 v37, v29, v145
	v_fmac_f32 v36, v24, v140
	v_fmac_f32 v37, v17, v137
	v_mul_f32_e32 v34, v34, v41
	v_mul_f32_e32 v41, 0xbfb8aa3b, v36
	v_fmac_f32 v37, v25, v141
	v_mul_f32_e32 v35, v35, v45
	v_exp_f32_e32 v41, v41
	v_mul_f32_e32 v45, 0xbfb8aa3b, v37
	v_exp_f32_e32 v45, v45
	v_mul_f32_e32 v34, v54, v34
	v_add_f32_e32 v41, 1.0, v41
	v_rcp_f32_e32 v41, v41
	v_add_f32_e32 v45, 1.0, v45
	v_rcp_f32_e32 v45, v45
	v_mul_f32_e32 v35, v52, v35
	v_cvt_pk_bf16_f32 v48, v34, v35
	v_mul_f32_e32 v35, v36, v41
	v_mul_f32_e32 v35, v53, v35
	v_mul_f32_e32 v36, v37, v45
	v_mul_f32_e32 v36, v55, v36
	v_cvt_pk_bf16_f32 v49, v35, v36
	s_waitcnt lgkmcnt(0)
	global_store_dwordx4 v[96:97], v[46:49], off
	ds_read_addtid_b32 v46 offset:24576
	ds_read_addtid_b32 v47 offset:24832
	v_mul_f32_e32 v34, v22, v142
	v_fmac_f32 v34, v26, v134
	v_mul_f32_e32 v26, v23, v143
	v_fmac_f32 v34, v18, v138
	v_fmac_f32 v26, v27, v135
	v_mul_f32_e32 v27, v24, v144
	v_mul_f32_e32 v35, 0xbfb8aa3b, v34
	v_fmac_f32 v26, v19, v139
	v_exp_f32_e32 v35, v35
	v_mul_f32_e32 v36, 0xbfb8aa3b, v26
	v_exp_f32_e32 v36, v36
	v_fmac_f32 v27, v28, v136
	v_mul_f32_e32 v28, v25, v145
	v_fmac_f32 v28, v29, v137
	v_add_f32_e32 v29, 1.0, v35
	v_rcp_f32_e32 v29, v29
	v_add_f32_e32 v35, 1.0, v36
	v_rcp_f32_e32 v35, v35
	v_fmac_f32 v27, v20, v140
	v_mul_f32_e32 v29, v34, v29
	v_mul_f32_e32 v34, 0xbfb8aa3b, v27
	v_fmac_f32 v28, v21, v141
	v_mul_f32_e32 v26, v26, v35
	v_exp_f32_e32 v34, v34
	v_mul_f32_e32 v35, 0xbfb8aa3b, v28
	v_exp_f32_e32 v35, v35
	v_mul_f32_e32 v26, v50, v26
	v_add_f32_e32 v34, 1.0, v34
	v_rcp_f32_e32 v34, v34
	v_add_f32_e32 v35, 1.0, v35
	v_rcp_f32_e32 v35, v35
	v_mul_f32_e32 v29, v51, v29
	v_mul_f32_e32 v27, v27, v34
	v_mul_f32_e32 v27, v43, v27
	v_mul_f32_e32 v28, v28, v35
	v_cvt_pk_bf16_f32 v48, v29, v26
	v_mul_f32_e32 v28, v44, v28
	v_cvt_pk_bf16_f32 v49, v27, v28
	s_waitcnt lgkmcnt(0)
	global_store_dwordx4 v[90:91], v[46:49], off
	ds_read_addtid_b32 v34 offset:25088
	ds_read_addtid_b32 v35 offset:25344
	v_mul_f32_e32 v18, v142, v18
	v_fmac_f32 v18, v22, v134
	s_nop 0
	v_fmac_f32_dpp v18, v14, v138 row_shl:1 row_mask:0xf bank_mask:0xf
	v_mul_f32_e32 v14, v143, v19
	v_fmac_f32 v14, v23, v135
	v_fmac_f32_e32 v18, v138, v30
	v_fmac_f32_dpp v14, v15, v139 row_shl:1 row_mask:0xf bank_mask:0xf
	v_mul_f32_e32 v19, 0xbfb8aa3b, v18
	v_fmac_f32_e32 v14, v139, v31
	v_mul_f32_e32 v15, v144, v20
	v_exp_f32_e32 v19, v19
	v_mul_f32_e32 v20, 0xbfb8aa3b, v14
	v_fmac_f32 v15, v24, v136
	v_exp_f32_e32 v20, v20
	v_fmac_f32_dpp v15, v16, v140 row_shl:1 row_mask:0xf bank_mask:0xf
	v_mul_f32_e32 v16, v145, v21
	v_fmac_f32 v16, v25, v137
	v_fmac_f32_e32 v15, v140, v32
	v_fmac_f32_dpp v16, v17, v141 row_shl:1 row_mask:0xf bank_mask:0xf
	v_add_f32_e32 v17, 1.0, v19
	v_rcp_f32_e32 v17, v17
	v_add_f32_e32 v19, 1.0, v20
	v_rcp_f32_e32 v19, v19
	v_fmac_f32_e32 v16, v141, v33
	v_mul_f32_e32 v17, v18, v17
	v_mul_f32_e32 v18, 0xbfb8aa3b, v15
	v_mul_f32_e32 v14, v14, v19
	v_exp_f32_e32 v18, v18
	v_mul_f32_e32 v19, 0xbfb8aa3b, v16
	v_exp_f32_e32 v19, v19
	v_mul_f32_e32 v14, v38, v14
	v_add_f32_e32 v18, 1.0, v18
	v_rcp_f32_e32 v18, v18
	v_add_f32_e32 v19, 1.0, v19
	v_rcp_f32_e32 v19, v19
	v_mul_f32_e32 v17, v42, v17
	v_mul_f32_e32 v15, v15, v18
	v_mul_f32_e32 v15, v39, v15
	v_mul_f32_e32 v16, v16, v19
	v_cvt_pk_bf16_f32 v36, v17, v14
	v_mul_f32_e32 v16, v40, v16
	v_cvt_pk_bf16_f32 v37, v15, v16
	s_and_saveexec_b64 s[8:9], s[66:67]
	s_cbranch_execz .LBB0_1514
	v_mov_b64_e32 v[16:17], s[42:43]
	v_mad_i64_i32 v[16:17], s[0:1], v78, s90, v[16:17]
	v_lshl_add_u64 v[16:17], v[4:5], 1, v[16:17]
	s_waitcnt lgkmcnt(0)
	global_store_dwordx4 v[16:17], v[34:37], off

	.amdhsa_kernel _Z10fwd_kernel4Args
		.amdhsa_group_segment_fixed_size 0
		.amdhsa_private_segment_fixed_size 0
		.amdhsa_kernarg_size 192
		.amdhsa_user_sgpr_count 2
		.amdhsa_user_sgpr_dispatch_ptr 0
		.amdhsa_user_sgpr_queue_ptr 0
		.amdhsa_user_sgpr_kernarg_segment_ptr 1
		.amdhsa_user_sgpr_dispatch_id 0
		.amdhsa_user_sgpr_kernarg_preload_length 0
		.amdhsa_user_sgpr_kernarg_preload_offset 0
		.amdhsa_user_sgpr_private_segment_size 0
		.amdhsa_uses_dynamic_stack 0
		.amdhsa_enable_private_segment 0
		.amdhsa_system_sgpr_workgroup_id_x 1
		.amdhsa_system_sgpr_workgroup_id_y 0
		.amdhsa_system_sgpr_workgroup_id_z 0
		.amdhsa_system_sgpr_workgroup_info 0
		.amdhsa_system_vgpr_workitem_id 0
		.amdhsa_next_free_vgpr 254
		.amdhsa_next_free_sgpr 102
		.amdhsa_accum_offset 256
		.amdhsa_reserve_vcc 1
		.amdhsa_float_round_mode_32 0
		.amdhsa_float_round_mode_16_64 0
		.amdhsa_float_denorm_mode_32 3
		.amdhsa_float_denorm_mode_16_64 3
		.amdhsa_dx10_clamp 1
		.amdhsa_ieee_mode 1
		.amdhsa_fp16_overflow 0
		.amdhsa_tg_split 0
		.amdhsa_exception_fp_ieee_invalid_op 0
		.amdhsa_exception_fp_denorm_src 0
		.amdhsa_exception_fp_ieee_div_zero 0
		.amdhsa_exception_fp_ieee_overflow 0
		.amdhsa_exception_fp_ieee_underflow 0
		.amdhsa_exception_fp_ieee_inexact 0
		.amdhsa_exception_int_div_zero 0
	.end_amdhsa_kernel

amdhsa.kernels:
  - .agpr_count:     0
    .args:
      - .offset:         0
        .size:           192
        .value_kind:     by_value
    .group_segment_fixed_size: 0
    .kernarg_segment_align: 8
    .kernarg_segment_size: 192
    .language:       OpenCL C
    .language_version:
      - 2
      - 0
    .max_flat_workgroup_size: 512
    .name:           _Z10fwd_kernel4Args
    .private_segment_fixed_size: 0
    .sgpr_count:     108
    .sgpr_spill_count: 67
    .symbol:         _Z10fwd_kernel4Args.kd
    .uniform_work_group_size: 1
    .uses_dynamic_stack: false
    .vgpr_count:     254
    .vgpr_spill_count: 0
    .wavefront_size: 64
